# s_setprio flips removed from the four GEMM K-loops (on the cache-policy + stagger version)
# speedup vs baseline: 1.0496x; 1.0013x over previous
; #define PG8_STAGE(bufoff, gbase, voff) do { _Pragma("unroll") for (int _i = 0; _i < 2; ++_i) \
;         __builtin_amdgcn_global_load_lds((const unsigned*)((const char*)(gbase) + (voff)[_i]), (PG8_LAS unsigned*)(lds + (bufoff) + ldsw + _i * 8192), 16, 0, 0); } while (0)
; #define PG8_LDA(dst, b, h) do { _Pragma("unroll") for (int m = 0; m < 4; ++m) _Pragma("unroll") for (int k = 0; k < 2; ++k) dst[m][k] = *(const PG8_LAS bf16x8*)(lds + PG8_SA(b, h) + aoff + m * 2048 + k * 1024); } while (0)
; #define PG8_LDB(dst, b, h) do { _Pragma("unroll") for (int n = 0; n < 2; ++n) _Pragma("unroll") for (int k = 0; k < 2; ++k) dst[n][k] = *(const PG8_LAS bf16x8*)(lds + PG8_SB(b, h) + boff + n * 2048 + k * 1024); } while (0)
; #define PG8_MMA(ai, bj, At, Bt) do { __builtin_amdgcn_s_setprio(1); _Pragma("unroll") for (int m = 0; m < 4; ++m) _Pragma("unroll") for (int n = 0; n < 2; ++n) _Pragma("unroll") for (int k = 0; k < 2; ++k) \
;         acc[ai][bj][m][n] = __builtin_amdgcn_mfma_f32_16x16x32_bf16(Bt[n][k], At[m][k], acc[ai][bj][m][n], 0, 0, 0); __builtin_amdgcn_s_setprio(0); } while (0)
; #define PG8_WAIT_V(n) asm volatile("s_waitcnt vmcnt(" #n ")" ::: "memory")
; #define PG8_WAIT_L(n) asm volatile("s_waitcnt lgkmcnt(" #n ")" ::: "memory")
; #define PG8_BAR __builtin_amdgcn_s_barrier()
; #define PG8_SCHED __builtin_amdgcn_sched_barrier(0)
; template <class Epi, class Sched, bool ALIGN_EPI = false, bool SP2 = false>
; __device__ __forceinline__ void gemm_phase(PG8_LAS unsigned char* lds, const Gemm g, const Sched& S, const Epi& E) {
;     ...
;             PG8_LDB(B0, 0, 0); PG8_LDB(B1, 0, 1); PG8_SCHED; PG8_LDA(At, 0, 0); PG8_STAGE(PG8_SA(1, 1), a1 + hstep, voffA);
;             PG8_WAIT_V(8); PG8_WAIT_L(0); PG8_BAR; PG8_MMA(0, 0, At, B0); PG8_MMA(0, 1, At, B1); PG8_BAR; PG8_SCHED;
;             PG8_LDA(At, 0, 1); PG8_STAGE(PG8_SB(0, 0), b2, voffB); PG8_STAGE(PG8_SB(0, 1), b2 + hstep, voffB); PG8_STAGE(PG8_SA(0, 0), a2, voffA);
.LBB0_102:
	ds_read_b128 v[148:151], v156
	ds_read_b128 v[160:163], v156 offset:1024
	ds_read_b128 v[164:167], v156 offset:2048
	ds_read_b128 v[168:171], v156 offset:3072
	ds_read_b128 v[172:175], v157
	ds_read_b128 v[176:179], v157 offset:1024
	ds_read_b128 v[180:183], v157 offset:2048
	ds_read_b128 v[184:187], v157 offset:3072
	s_add_u32 s68, s66, 0xfffc0080
	s_addc_u32 s69, s67, -1
	s_cmp_eq_u32 s92, 12
	s_cselect_b32 s71, s5, s69
	s_cselect_b32 s70, s19, s68
	s_cselect_b32 s69, s17, s91
	s_cselect_b32 s68, s72, s73
	v_lshl_add_u64 v[152:153], s[66:67], 0, v[140:141]
	s_add_i32 m0, s65, 0xc000
	ds_read_b128 v[188:191], v158
	ds_read_b128 v[192:195], v158 offset:1024
	ds_read_b128 v[196:199], v158 offset:2048
	ds_read_b128 v[200:203], v158 offset:3072
	ds_read_b128 v[204:207], v158 offset:4096
	ds_read_b128 v[208:211], v158 offset:5120
	ds_read_b128 v[212:215], v158 offset:6144
	ds_read_b128 v[216:219], v158 offset:7168
	global_load_lds_dwordx4 v[152:153], off
	v_lshl_add_u64 v[152:153], s[66:67], 0, v[142:143]
	s_add_i32 m0, s65, 0xe000
	s_nop 0
	global_load_lds_dwordx4 v[152:153], off
	s_waitcnt vmcnt(8)
	s_waitcnt lgkmcnt(0)
	s_barrier
	s_waitcnt lgkmcnt(0)
	v_mfma_f32_16x16x32_bf16 v[126:129], v[148:151], v[188:191], v[126:129]
	v_mfma_f32_16x16x32_bf16 v[122:125], v[164:167], v[188:191], v[122:125]
	v_mfma_f32_16x16x32_bf16 v[110:113], v[148:151], v[196:199], v[110:113]
	v_mfma_f32_16x16x32_bf16 v[106:109], v[164:167], v[196:199], v[106:109]
	v_mfma_f32_16x16x32_bf16 v[94:97], v[148:151], v[204:207], v[94:97]
	v_mfma_f32_16x16x32_bf16 v[90:93], v[164:167], v[204:207], v[90:93]
	v_mfma_f32_16x16x32_bf16 v[78:81], v[148:151], v[212:215], v[78:81]
	v_mfma_f32_16x16x32_bf16 v[74:77], v[164:167], v[212:215], v[74:77]
	v_mfma_f32_16x16x32_bf16 v[126:129], v[160:163], v[192:195], v[126:129]
	v_mfma_f32_16x16x32_bf16 v[122:125], v[168:171], v[192:195], v[122:125]
	v_mfma_f32_16x16x32_bf16 v[110:113], v[160:163], v[200:203], v[110:113]
	v_mfma_f32_16x16x32_bf16 v[106:109], v[168:171], v[200:203], v[106:109]
	v_mfma_f32_16x16x32_bf16 v[94:97], v[160:163], v[208:211], v[94:97]
	v_mfma_f32_16x16x32_bf16 v[90:93], v[168:171], v[208:211], v[90:93]
	v_mfma_f32_16x16x32_bf16 v[78:81], v[160:163], v[216:219], v[78:81]
	v_mfma_f32_16x16x32_bf16 v[74:77], v[168:171], v[216:219], v[74:77]
	v_mfma_f32_16x16x32_bf16 v[118:121], v[172:175], v[188:191], v[118:121]
	v_mfma_f32_16x16x32_bf16 v[114:117], v[180:183], v[188:191], v[114:117]
	v_mfma_f32_16x16x32_bf16 v[102:105], v[172:175], v[196:199], v[102:105]
	v_mfma_f32_16x16x32_bf16 v[98:101], v[180:183], v[196:199], v[98:101]
	v_mfma_f32_16x16x32_bf16 v[86:89], v[172:175], v[204:207], v[86:89]
	v_mfma_f32_16x16x32_bf16 v[82:85], v[180:183], v[204:207], v[82:85]
	v_mfma_f32_16x16x32_bf16 v[70:73], v[172:175], v[212:215], v[70:73]
	v_mfma_f32_16x16x32_bf16 v[66:69], v[180:183], v[212:215], v[66:69]
	v_mfma_f32_16x16x32_bf16 v[118:121], v[176:179], v[192:195], v[118:121]
	v_mfma_f32_16x16x32_bf16 v[114:117], v[184:187], v[192:195], v[114:117]
	v_mfma_f32_16x16x32_bf16 v[102:105], v[176:179], v[200:203], v[102:105]
	v_mfma_f32_16x16x32_bf16 v[98:101], v[184:187], v[200:203], v[98:101]
	v_mfma_f32_16x16x32_bf16 v[86:89], v[176:179], v[208:211], v[86:89]
	v_mfma_f32_16x16x32_bf16 v[82:85], v[184:187], v[208:211], v[82:85]
	v_mfma_f32_16x16x32_bf16 v[70:73], v[176:179], v[216:219], v[70:73]
	v_mfma_f32_16x16x32_bf16 v[66:69], v[184:187], v[216:219], v[66:69]
	s_barrier
	s_add_i32 s93, s89, s76
	v_lshl_add_u64 v[152:153], s[68:69], 0, v[132:133]
	s_mov_b32 m0, s93
	ds_read_b128 v[188:191], v158 offset:16384
	ds_read_b128 v[192:195], v158 offset:17408
	ds_read_b128 v[196:199], v158 offset:18432
	ds_read_b128 v[200:203], v158 offset:19456
	ds_read_b128 v[204:207], v158 offset:20480
	ds_read_b128 v[208:211], v158 offset:21504
	ds_read_b128 v[212:215], v158 offset:22528
	ds_read_b128 v[216:219], v158 offset:23552
	global_load_lds_dwordx4 v[152:153], off
	s_add_i32 m0, s93, 0x2000
	s_add_u32 s94, s68, 0x40000
	v_lshl_add_u64 v[220:221], s[68:69], 0, v[136:137]
	s_addc_u32 s95, s69, 0
	s_add_i32 s93, s90, s76
	global_load_lds_dwordx4 v[220:221], off
	v_lshl_add_u64 v[222:223], s[94:95], 0, v[132:133]
	s_mov_b32 m0, s93
	v_lshl_add_u64 v[224:225], s[70:71], 0, v[134:135]
	global_load_lds_dwordx4 v[222:223], off
	v_lshl_add_u64 v[222:223], s[94:95], 0, v[136:137]
	s_add_i32 m0, s93, 0x2000
	s_nop 0
	global_load_lds_dwordx4 v[222:223], off
	v_lshl_add_u64 v[222:223], s[70:71], 0, v[130:131]
	s_mov_b32 m0, s65
	s_nop 0
	global_load_lds_dwordx4 v[222:223], off
	s_mov_b32 m0, s77
	s_nop 0
	global_load_lds_dwordx4 v[224:225], off
	s_waitcnt vmcnt(8)
	s_waitcnt lgkmcnt(0)
	s_barrier
; #define PG8_STAGE(bufoff, gbase, voff) do { _Pragma("unroll") for (int _i = 0; _i < 2; ++_i) \
;         __builtin_amdgcn_global_load_lds((const unsigned*)((const char*)(gbase) + (voff)[_i]), (PG8_LAS unsigned*)(lds + (bufoff) + ldsw + _i * 8192), 16, 0, 0); } while (0)
; #define PG8_LDA(dst, b, h) do { _Pragma("unroll") for (int m = 0; m < 4; ++m) _Pragma("unroll") for (int k = 0; k < 2; ++k) dst[m][k] = *(const PG8_LAS bf16x8*)(lds + PG8_SA(b, h) + aoff + m * 2048 + k * 1024); } while (0)
; #define PG8_LDB(dst, b, h) do { _Pragma("unroll") for (int n = 0; n < 2; ++n) _Pragma("unroll") for (int k = 0; k < 2; ++k) dst[n][k] = *(const PG8_LAS bf16x8*)(lds + PG8_SB(b, h) + boff + n * 2048 + k * 1024); } while (0)
; #define PG8_MMA(ai, bj, At, Bt) do { __builtin_amdgcn_s_setprio(1); _Pragma("unroll") for (int m = 0; m < 4; ++m) _Pragma("unroll") for (int n = 0; n < 2; ++n) _Pragma("unroll") for (int k = 0; k < 2; ++k) \
;         acc[ai][bj][m][n] = __builtin_amdgcn_mfma_f32_16x16x32_bf16(Bt[n][k], At[m][k], acc[ai][bj][m][n], 0, 0, 0); __builtin_amdgcn_s_setprio(0); } while (0)
; #define PG8_WAIT_V(n) asm volatile("s_waitcnt vmcnt(" #n ")" ::: "memory")
; #define PG8_WAIT_L(n) asm volatile("s_waitcnt lgkmcnt(" #n ")" ::: "memory")
; #define PG8_BAR __builtin_amdgcn_s_barrier()
; #define PG8_SCHED __builtin_amdgcn_sched_barrier(0)
; template <class Epi, class Sched, bool ALIGN_EPI = false, bool SP2 = false>
; __device__ __forceinline__ void gemm_phase(PG8_LAS unsigned char* lds, const Gemm g, const Sched& S, const Epi& E) {
;     ...
;             PG8_WAIT_V(8); PG8_WAIT_L(0); PG8_BAR; PG8_MMA(1, 0, At, B0); PG8_MMA(1, 1, At, B1); PG8_BAR; PG8_SCHED;
;             PG8_LDB(B0, 1, 0); PG8_LDB(B1, 1, 1); PG8_SCHED; PG8_LDA(At, 1, 0); PG8_STAGE(PG8_SA(0, 1), a2 + hstep, voffA);
;             PG8_WAIT_V(8); PG8_WAIT_L(0); PG8_BAR; PG8_MMA(0, 0, At, B0); PG8_MMA(0, 1, At, B1); PG8_BAR; PG8_SCHED;
;             PG8_LDA(At, 1, 1); PG8_STAGE(PG8_SB(1, 0), b3, voffB); PG8_STAGE(PG8_SB(1, 1), b3 + hstep, voffB); PG8_STAGE(PG8_SA(1, 0), a3, voffA);
	s_waitcnt lgkmcnt(0)
	v_mfma_f32_16x16x32_bf16 v[62:65], v[148:151], v[188:191], v[62:65]
	v_mfma_f32_16x16x32_bf16 v[58:61], v[164:167], v[188:191], v[58:61]
	v_mfma_f32_16x16x32_bf16 v[46:49], v[148:151], v[196:199], v[46:49]
	v_mfma_f32_16x16x32_bf16 v[42:45], v[164:167], v[196:199], v[42:45]
	v_mfma_f32_16x16x32_bf16 v[30:33], v[148:151], v[204:207], v[30:33]
	v_mfma_f32_16x16x32_bf16 v[26:29], v[164:167], v[204:207], v[26:29]
	v_mfma_f32_16x16x32_bf16 v[14:17], v[148:151], v[212:215], v[14:17]
	v_mfma_f32_16x16x32_bf16 v[10:13], v[164:167], v[212:215], v[10:13]
	v_mfma_f32_16x16x32_bf16 v[62:65], v[160:163], v[192:195], v[62:65]
	v_mfma_f32_16x16x32_bf16 v[58:61], v[168:171], v[192:195], v[58:61]
	v_mfma_f32_16x16x32_bf16 v[46:49], v[160:163], v[200:203], v[46:49]
	v_mfma_f32_16x16x32_bf16 v[42:45], v[168:171], v[200:203], v[42:45]
	v_mfma_f32_16x16x32_bf16 v[30:33], v[160:163], v[208:211], v[30:33]
	v_mfma_f32_16x16x32_bf16 v[26:29], v[168:171], v[208:211], v[26:29]
	v_mfma_f32_16x16x32_bf16 v[14:17], v[160:163], v[216:219], v[14:17]
	v_mfma_f32_16x16x32_bf16 v[10:13], v[168:171], v[216:219], v[10:13]
	v_mfma_f32_16x16x32_bf16 v[54:57], v[172:175], v[188:191], v[54:57]
	v_mfma_f32_16x16x32_bf16 v[50:53], v[180:183], v[188:191], v[50:53]
	v_mfma_f32_16x16x32_bf16 v[38:41], v[172:175], v[196:199], v[38:41]
	v_mfma_f32_16x16x32_bf16 v[34:37], v[180:183], v[196:199], v[34:37]
	v_mfma_f32_16x16x32_bf16 v[22:25], v[172:175], v[204:207], v[22:25]
	v_mfma_f32_16x16x32_bf16 v[18:21], v[180:183], v[204:207], v[18:21]
	v_mfma_f32_16x16x32_bf16 v[6:9], v[172:175], v[212:215], v[6:9]
	v_mfma_f32_16x16x32_bf16 v[2:5], v[180:183], v[212:215], v[2:5]
	v_mfma_f32_16x16x32_bf16 v[54:57], v[176:179], v[192:195], v[54:57]
	v_mfma_f32_16x16x32_bf16 v[50:53], v[184:187], v[192:195], v[50:53]
	v_mfma_f32_16x16x32_bf16 v[38:41], v[176:179], v[200:203], v[38:41]
	v_mfma_f32_16x16x32_bf16 v[34:37], v[184:187], v[200:203], v[34:37]
	v_mfma_f32_16x16x32_bf16 v[22:25], v[176:179], v[208:211], v[22:25]
	v_mfma_f32_16x16x32_bf16 v[18:21], v[184:187], v[208:211], v[18:21]
	v_mfma_f32_16x16x32_bf16 v[6:9], v[176:179], v[216:219], v[6:9]
	v_mfma_f32_16x16x32_bf16 v[2:5], v[184:187], v[216:219], v[2:5]
	s_barrier
	s_add_i32 s93, 0, 0x18000
	v_add_u32_e32 v138, s93, v154
	s_add_i32 s94, 0, 0x1c000
	ds_read_b128 v[148:151], v138
	ds_read_b128 v[160:163], v138 offset:1024
	ds_read_b128 v[164:167], v138 offset:2048
	ds_read_b128 v[168:171], v138 offset:3072
	v_add_u32_e32 v138, s94, v154
	ds_read_b128 v[172:175], v138
	ds_read_b128 v[176:179], v138 offset:1024
	ds_read_b128 v[180:183], v138 offset:2048
	ds_read_b128 v[184:187], v138 offset:3072
	s_add_u32 s70, s70, 0x40000
	s_addc_u32 s71, s71, 0
	s_mov_b32 m0, s78
	v_lshl_add_u64 v[226:227], s[70:71], 0, v[130:131]
	ds_read_b128 v[188:191], v158 offset:32768
	ds_read_b128 v[192:195], v158 offset:33792
	ds_read_b128 v[196:199], v158 offset:34816
	ds_read_b128 v[200:203], v158 offset:35840
	ds_read_b128 v[204:207], v158 offset:36864
	ds_read_b128 v[208:211], v158 offset:37888
	ds_read_b128 v[212:215], v158 offset:38912
	ds_read_b128 v[216:219], v158 offset:39936
	global_load_lds_dwordx4 v[226:227], off
	v_lshl_add_u64 v[226:227], s[70:71], 0, v[134:135]
	s_mov_b32 m0, s79
	s_nop 0
	global_load_lds_dwordx4 v[226:227], off
	s_waitcnt vmcnt(8)
	s_waitcnt lgkmcnt(0)
	s_barrier
	s_waitcnt lgkmcnt(0)
	v_mfma_f32_16x16x32_bf16 v[126:129], v[148:151], v[188:191], v[126:129]
	v_mfma_f32_16x16x32_bf16 v[122:125], v[164:167], v[188:191], v[122:125]
	v_mfma_f32_16x16x32_bf16 v[110:113], v[148:151], v[196:199], v[110:113]
	v_mfma_f32_16x16x32_bf16 v[106:109], v[164:167], v[196:199], v[106:109]
	v_mfma_f32_16x16x32_bf16 v[94:97], v[148:151], v[204:207], v[94:97]
	v_mfma_f32_16x16x32_bf16 v[90:93], v[164:167], v[204:207], v[90:93]
	v_mfma_f32_16x16x32_bf16 v[78:81], v[148:151], v[212:215], v[78:81]
	v_mfma_f32_16x16x32_bf16 v[74:77], v[164:167], v[212:215], v[74:77]
	v_mfma_f32_16x16x32_bf16 v[126:129], v[160:163], v[192:195], v[126:129]
	v_mfma_f32_16x16x32_bf16 v[122:125], v[168:171], v[192:195], v[122:125]
	v_mfma_f32_16x16x32_bf16 v[110:113], v[160:163], v[200:203], v[110:113]
	v_mfma_f32_16x16x32_bf16 v[106:109], v[168:171], v[200:203], v[106:109]
	v_mfma_f32_16x16x32_bf16 v[94:97], v[160:163], v[208:211], v[94:97]
	v_mfma_f32_16x16x32_bf16 v[90:93], v[168:171], v[208:211], v[90:93]
	v_mfma_f32_16x16x32_bf16 v[78:81], v[160:163], v[216:219], v[78:81]
	v_mfma_f32_16x16x32_bf16 v[74:77], v[168:171], v[216:219], v[74:77]
	v_mfma_f32_16x16x32_bf16 v[118:121], v[172:175], v[188:191], v[118:121]
	v_mfma_f32_16x16x32_bf16 v[114:117], v[180:183], v[188:191], v[114:117]
	v_mfma_f32_16x16x32_bf16 v[102:105], v[172:175], v[196:199], v[102:105]
	v_mfma_f32_16x16x32_bf16 v[98:101], v[180:183], v[196:199], v[98:101]
	v_mfma_f32_16x16x32_bf16 v[86:89], v[172:175], v[204:207], v[86:89]
	v_mfma_f32_16x16x32_bf16 v[82:85], v[180:183], v[204:207], v[82:85]
	v_mfma_f32_16x16x32_bf16 v[70:73], v[172:175], v[212:215], v[70:73]
	v_mfma_f32_16x16x32_bf16 v[66:69], v[180:183], v[212:215], v[66:69]
	v_mfma_f32_16x16x32_bf16 v[118:121], v[176:179], v[192:195], v[118:121]
	v_mfma_f32_16x16x32_bf16 v[114:117], v[184:187], v[192:195], v[114:117]
	v_mfma_f32_16x16x32_bf16 v[102:105], v[176:179], v[200:203], v[102:105]
	v_mfma_f32_16x16x32_bf16 v[98:101], v[184:187], v[200:203], v[98:101]
	v_mfma_f32_16x16x32_bf16 v[86:89], v[176:179], v[208:211], v[86:89]
	v_mfma_f32_16x16x32_bf16 v[82:85], v[184:187], v[208:211], v[82:85]
	v_mfma_f32_16x16x32_bf16 v[70:73], v[176:179], v[216:219], v[70:73]
	v_mfma_f32_16x16x32_bf16 v[66:69], v[184:187], v[216:219], v[66:69]
	s_barrier
; #define PG8_STAGE(bufoff, gbase, voff) do { _Pragma("unroll") for (int _i = 0; _i < 2; ++_i) \
;         __builtin_amdgcn_global_load_lds((const unsigned*)((const char*)(gbase) + (voff)[_i]), (PG8_LAS unsigned*)(lds + (bufoff) + ldsw + _i * 8192), 16, 0, 0); } while (0)
; #define PG8_LDA(dst, b, h) do { _Pragma("unroll") for (int m = 0; m < 4; ++m) _Pragma("unroll") for (int k = 0; k < 2; ++k) dst[m][k] = *(const PG8_LAS bf16x8*)(lds + PG8_SA(b, h) + aoff + m * 2048 + k * 1024); } while (0)
; #define PG8_MMA(ai, bj, At, Bt) do { __builtin_amdgcn_s_setprio(1); _Pragma("unroll") for (int m = 0; m < 4; ++m) _Pragma("unroll") for (int n = 0; n < 2; ++n) _Pragma("unroll") for (int k = 0; k < 2; ++k) \
;         acc[ai][bj][m][n] = __builtin_amdgcn_mfma_f32_16x16x32_bf16(Bt[n][k], At[m][k], acc[ai][bj][m][n], 0, 0, 0); __builtin_amdgcn_s_setprio(0); } while (0)
; #define PG8_WAIT_V(n) asm volatile("s_waitcnt vmcnt(" #n ")" ::: "memory")
; #define PG8_WAIT_L(n) asm volatile("s_waitcnt lgkmcnt(" #n ")" ::: "memory")
; #define PG8_BAR __builtin_amdgcn_s_barrier()
; #define PG8_SCHED __builtin_amdgcn_sched_barrier(0)
; template <class Epi, class Sched, bool ALIGN_EPI = false, bool SP2 = false>
; __device__ __forceinline__ void gemm_phase(PG8_LAS unsigned char* lds, const Gemm g, const Sched& S, const Epi& E) {
;     ...
;         for (int t = 0; t < nt; t += 2) {
;     ...
;             PG8_LDA(At, 1, 1); PG8_STAGE(PG8_SB(1, 0), b3, voffB); PG8_STAGE(PG8_SB(1, 1), b3 + hstep, voffB); PG8_STAGE(PG8_SA(1, 0), a3, voffA);
;             PG8_WAIT_V(8); PG8_WAIT_L(0); PG8_BAR; PG8_MMA(1, 0, At, B0); PG8_MMA(1, 1, At, B1); PG8_BAR; PG8_SCHED;
	s_add_i32 s70, s93, s76
	v_lshl_add_u64 v[152:153], v[152:153], 0, s[10:11]
	s_mov_b32 m0, s70
	ds_read_b128 v[188:191], v158 offset:49152
	ds_read_b128 v[192:195], v158 offset:50176
	ds_read_b128 v[196:199], v158 offset:51200
	ds_read_b128 v[200:203], v158 offset:52224
	ds_read_b128 v[204:207], v158 offset:53248
	ds_read_b128 v[208:211], v158 offset:54272
	ds_read_b128 v[212:215], v158 offset:55296
	ds_read_b128 v[216:219], v158 offset:56320
	global_load_lds_dwordx4 v[152:153], off
	s_add_i32 m0, s70, 0x2000
	s_add_u32 s68, s68, 0x40080
	v_lshl_add_u64 v[152:153], v[220:221], 0, s[10:11]
	s_addc_u32 s69, s69, 0
	s_add_i32 s70, s94, s76
	global_load_lds_dwordx4 v[152:153], off
	v_lshl_add_u64 v[152:153], s[68:69], 0, v[132:133]
	s_mov_b32 m0, s70
	s_nop 0
	global_load_lds_dwordx4 v[152:153], off
	v_lshl_add_u64 v[152:153], s[68:69], 0, v[136:137]
	s_add_i32 m0, s70, 0x2000
	s_nop 0
	global_load_lds_dwordx4 v[152:153], off
	v_lshl_add_u64 v[152:153], v[222:223], 0, s[10:11]
	s_mov_b32 m0, s81
	s_nop 0
	global_load_lds_dwordx4 v[152:153], off
	v_lshl_add_u64 v[152:153], v[224:225], 0, s[10:11]
	s_mov_b32 m0, s82
	s_nop 0
	global_load_lds_dwordx4 v[152:153], off
	s_waitcnt vmcnt(8)
	s_waitcnt lgkmcnt(0)
	s_barrier
	s_waitcnt lgkmcnt(0)
	v_mfma_f32_16x16x32_bf16 v[62:65], v[148:151], v[188:191], v[62:65]
	v_mfma_f32_16x16x32_bf16 v[58:61], v[164:167], v[188:191], v[58:61]
	v_mfma_f32_16x16x32_bf16 v[46:49], v[148:151], v[196:199], v[46:49]
	v_mfma_f32_16x16x32_bf16 v[42:45], v[164:167], v[196:199], v[42:45]
	v_mfma_f32_16x16x32_bf16 v[30:33], v[148:151], v[204:207], v[30:33]
	v_mfma_f32_16x16x32_bf16 v[26:29], v[164:167], v[204:207], v[26:29]
	v_mfma_f32_16x16x32_bf16 v[14:17], v[148:151], v[212:215], v[14:17]
	v_mfma_f32_16x16x32_bf16 v[10:13], v[164:167], v[212:215], v[10:13]
	v_mfma_f32_16x16x32_bf16 v[62:65], v[160:163], v[192:195], v[62:65]
	v_mfma_f32_16x16x32_bf16 v[58:61], v[168:171], v[192:195], v[58:61]
	v_mfma_f32_16x16x32_bf16 v[46:49], v[160:163], v[200:203], v[46:49]
	v_mfma_f32_16x16x32_bf16 v[42:45], v[168:171], v[200:203], v[42:45]
	v_mfma_f32_16x16x32_bf16 v[30:33], v[160:163], v[208:211], v[30:33]
	v_mfma_f32_16x16x32_bf16 v[26:29], v[168:171], v[208:211], v[26:29]
	v_mfma_f32_16x16x32_bf16 v[14:17], v[160:163], v[216:219], v[14:17]
	v_mfma_f32_16x16x32_bf16 v[10:13], v[168:171], v[216:219], v[10:13]
	v_mfma_f32_16x16x32_bf16 v[54:57], v[172:175], v[188:191], v[54:57]
	v_mfma_f32_16x16x32_bf16 v[50:53], v[180:183], v[188:191], v[50:53]
	v_mfma_f32_16x16x32_bf16 v[38:41], v[172:175], v[196:199], v[38:41]
	v_mfma_f32_16x16x32_bf16 v[34:37], v[180:183], v[196:199], v[34:37]
	v_mfma_f32_16x16x32_bf16 v[22:25], v[172:175], v[204:207], v[22:25]
	v_mfma_f32_16x16x32_bf16 v[18:21], v[180:183], v[204:207], v[18:21]
	v_mfma_f32_16x16x32_bf16 v[6:9], v[172:175], v[212:215], v[6:9]
	v_mfma_f32_16x16x32_bf16 v[2:5], v[180:183], v[212:215], v[2:5]
	v_mfma_f32_16x16x32_bf16 v[54:57], v[176:179], v[192:195], v[54:57]
	v_mfma_f32_16x16x32_bf16 v[50:53], v[184:187], v[192:195], v[50:53]
	v_mfma_f32_16x16x32_bf16 v[38:41], v[176:179], v[200:203], v[38:41]
	v_mfma_f32_16x16x32_bf16 v[34:37], v[184:187], v[200:203], v[34:37]
	v_mfma_f32_16x16x32_bf16 v[22:25], v[176:179], v[208:211], v[22:25]
	v_mfma_f32_16x16x32_bf16 v[18:21], v[184:187], v[208:211], v[18:21]
	v_mfma_f32_16x16x32_bf16 v[6:9], v[176:179], v[216:219], v[6:9]
	v_mfma_f32_16x16x32_bf16 v[2:5], v[184:187], v[216:219], v[2:5]
	s_barrier
	s_add_i32 s92, s92, 2
	s_add_u32 s66, s66, 0x100
	s_addc_u32 s67, s67, 0
	s_add_u32 s73, s73, 0x100
	s_addc_u32 s91, s91, 0
	s_cmp_gt_u32 s92, 13
	s_cbranch_scc0 .LBB0_102
	s_and_b64 vcc, exec, s[12:13]
	s_cbranch_vccz .LBB0_105
	s_barrier

; #define PG8_STAGE(bufoff, gbase, voff) do { _Pragma("unroll") for (int _i = 0; _i < 2; ++_i) \
;         __builtin_amdgcn_global_load_lds((const unsigned*)((const char*)(gbase) + (voff)[_i]), (PG8_LAS unsigned*)(lds + (bufoff) + ldsw + _i * 8192), 16, 0, 0); } while (0)
; #define PG8_LDA(dst, b, h) do { _Pragma("unroll") for (int m = 0; m < 4; ++m) _Pragma("unroll") for (int k = 0; k < 2; ++k) dst[m][k] = *(const PG8_LAS bf16x8*)(lds + PG8_SA(b, h) + aoff + m * 2048 + k * 1024); } while (0)
; #define PG8_LDB(dst, b, h) do { _Pragma("unroll") for (int n = 0; n < 2; ++n) _Pragma("unroll") for (int k = 0; k < 2; ++k) dst[n][k] = *(const PG8_LAS bf16x8*)(lds + PG8_SB(b, h) + boff + n * 2048 + k * 1024); } while (0)
; #define PG8_MMA(ai, bj, At, Bt) do { __builtin_amdgcn_s_setprio(1); _Pragma("unroll") for (int m = 0; m < 4; ++m) _Pragma("unroll") for (int n = 0; n < 2; ++n) _Pragma("unroll") for (int k = 0; k < 2; ++k) \
;         acc[ai][bj][m][n] = __builtin_amdgcn_mfma_f32_16x16x32_bf16(Bt[n][k], At[m][k], acc[ai][bj][m][n], 0, 0, 0); __builtin_amdgcn_s_setprio(0); } while (0)
; #define PG8_WAIT_V(n) asm volatile("s_waitcnt vmcnt(" #n ")" ::: "memory")
; #define PG8_WAIT_L(n) asm volatile("s_waitcnt lgkmcnt(" #n ")" ::: "memory")
; #define PG8_BAR __builtin_amdgcn_s_barrier()
; #define PG8_SCHED __builtin_amdgcn_sched_barrier(0)
; template <class Epi, class Sched, bool ALIGN_EPI = false, bool SP2 = false>
; __device__ __forceinline__ void gemm_phase(PG8_LAS unsigned char* lds, const Gemm g, const Sched& S, const Epi& E) {
;     ...
;             PG8_LDB(B0, 0, 0); PG8_LDB(B1, 0, 1); PG8_SCHED; PG8_LDA(At, 0, 0); PG8_STAGE(PG8_SA(1, 1), a1 + hstep, voffA);
;             PG8_WAIT_V(8); PG8_WAIT_L(0); PG8_BAR; PG8_MMA(0, 0, At, B0); PG8_MMA(0, 1, At, B1); PG8_BAR; PG8_SCHED;
;             PG8_LDA(At, 0, 1); PG8_STAGE(PG8_SB(0, 0), b2, voffB); PG8_STAGE(PG8_SB(0, 1), b2 + hstep, voffB); PG8_STAGE(PG8_SA(0, 0), a2, voffA);
.LBB0_396:
	ds_read_b128 v[98:101], v172
	ds_read_b128 v[106:109], v172 offset:1024
	ds_read_b128 v[114:117], v172 offset:2048
	ds_read_b128 v[118:121], v172 offset:3072
	ds_read_b128 v[164:167], v173
	ds_read_b128 v[176:179], v173 offset:1024
	ds_read_b128 v[180:183], v173 offset:2048
	ds_read_b128 v[184:187], v173 offset:3072
	s_add_u32 s58, s56, 0xfffc0080
	s_addc_u32 s59, s57, -1
	s_cmp_eq_u32 s86, 12
	s_cselect_b32 s63, s43, s59
	s_cselect_b32 s62, s82, s58
	s_cselect_b32 s59, s23, s85
	s_cselect_b32 s58, s83, s84
	v_lshl_add_u64 v[168:169], s[56:57], 0, v[156:157]
	s_add_i32 m0, s55, 0xc000
	ds_read_b128 v[188:191], v174
	ds_read_b128 v[192:195], v174 offset:1024
	ds_read_b128 v[196:199], v174 offset:2048
	ds_read_b128 v[200:203], v174 offset:3072
	ds_read_b128 v[204:207], v174 offset:4096
	ds_read_b128 v[208:211], v174 offset:5120
	ds_read_b128 v[212:215], v174 offset:6144
	ds_read_b128 v[216:219], v174 offset:7168
	global_load_lds_dwordx4 v[168:169], off
	v_lshl_add_u64 v[168:169], s[56:57], 0, v[158:159]
	s_add_i32 m0, s55, 0xe000
	s_nop 0
	global_load_lds_dwordx4 v[168:169], off
	s_waitcnt vmcnt(8)
	s_waitcnt lgkmcnt(0)
	s_barrier
	s_waitcnt lgkmcnt(0)
	v_mfma_f32_16x16x32_bf16 v[142:145], v[98:101], v[188:191], v[142:145]
	v_mfma_f32_16x16x32_bf16 v[138:141], v[114:117], v[188:191], v[138:141]
	v_mfma_f32_16x16x32_bf16 v[126:129], v[98:101], v[196:199], v[126:129]
	v_mfma_f32_16x16x32_bf16 v[122:125], v[114:117], v[196:199], v[122:125]
	v_mfma_f32_16x16x32_bf16 v[94:97], v[98:101], v[204:207], v[94:97]
	v_mfma_f32_16x16x32_bf16 v[90:93], v[114:117], v[204:207], v[90:93]
	v_mfma_f32_16x16x32_bf16 v[78:81], v[98:101], v[212:215], v[78:81]
	v_mfma_f32_16x16x32_bf16 v[74:77], v[114:117], v[212:215], v[74:77]
	v_mfma_f32_16x16x32_bf16 v[142:145], v[106:109], v[192:195], v[142:145]
	v_mfma_f32_16x16x32_bf16 v[138:141], v[118:121], v[192:195], v[138:141]
	v_mfma_f32_16x16x32_bf16 v[126:129], v[106:109], v[200:203], v[126:129]
	v_mfma_f32_16x16x32_bf16 v[122:125], v[118:121], v[200:203], v[122:125]
	v_mfma_f32_16x16x32_bf16 v[94:97], v[106:109], v[208:211], v[94:97]
	v_mfma_f32_16x16x32_bf16 v[90:93], v[118:121], v[208:211], v[90:93]
	v_mfma_f32_16x16x32_bf16 v[78:81], v[106:109], v[216:219], v[78:81]
	v_mfma_f32_16x16x32_bf16 v[74:77], v[118:121], v[216:219], v[74:77]
	v_mfma_f32_16x16x32_bf16 v[134:137], v[164:167], v[188:191], v[134:137]
	v_mfma_f32_16x16x32_bf16 v[130:133], v[180:183], v[188:191], v[130:133]
	v_mfma_f32_16x16x32_bf16 v[110:113], v[164:167], v[196:199], v[110:113]
	v_mfma_f32_16x16x32_bf16 v[102:105], v[180:183], v[196:199], v[102:105]
	v_mfma_f32_16x16x32_bf16 v[86:89], v[164:167], v[204:207], v[86:89]
	v_mfma_f32_16x16x32_bf16 v[82:85], v[180:183], v[204:207], v[82:85]
	v_mfma_f32_16x16x32_bf16 v[70:73], v[164:167], v[212:215], v[70:73]
	v_mfma_f32_16x16x32_bf16 v[66:69], v[180:183], v[212:215], v[66:69]
	v_mfma_f32_16x16x32_bf16 v[134:137], v[176:179], v[192:195], v[134:137]
	v_mfma_f32_16x16x32_bf16 v[130:133], v[184:187], v[192:195], v[130:133]
	v_mfma_f32_16x16x32_bf16 v[110:113], v[176:179], v[200:203], v[110:113]
	v_mfma_f32_16x16x32_bf16 v[102:105], v[184:187], v[200:203], v[102:105]
	v_mfma_f32_16x16x32_bf16 v[86:89], v[176:179], v[208:211], v[86:89]
	v_mfma_f32_16x16x32_bf16 v[82:85], v[184:187], v[208:211], v[82:85]
	v_mfma_f32_16x16x32_bf16 v[70:73], v[176:179], v[216:219], v[70:73]
	v_mfma_f32_16x16x32_bf16 v[66:69], v[184:187], v[216:219], v[66:69]
	s_barrier
	s_add_i32 s87, s75, s67
	v_lshl_add_u64 v[168:169], s[58:59], 0, v[148:149]
	s_mov_b32 m0, s87
	ds_read_b128 v[188:191], v174 offset:16384
	ds_read_b128 v[192:195], v174 offset:17408
	ds_read_b128 v[196:199], v174 offset:18432
	ds_read_b128 v[200:203], v174 offset:19456
	ds_read_b128 v[204:207], v174 offset:20480
	ds_read_b128 v[208:211], v174 offset:21504
	ds_read_b128 v[212:215], v174 offset:22528
	ds_read_b128 v[216:219], v174 offset:23552
	global_load_lds_dwordx4 v[168:169], off
	s_add_i32 m0, s87, 0x2000
	s_add_u32 s88, s58, 0x40000
	v_lshl_add_u64 v[220:221], s[58:59], 0, v[152:153]
	s_addc_u32 s89, s59, 0
	s_add_i32 s87, s76, s67
	global_load_lds_dwordx4 v[220:221], off
	v_lshl_add_u64 v[222:223], s[88:89], 0, v[148:149]
	s_mov_b32 m0, s87
	v_lshl_add_u64 v[224:225], s[62:63], 0, v[150:151]
	global_load_lds_dwordx4 v[222:223], off
	v_lshl_add_u64 v[222:223], s[88:89], 0, v[152:153]
	s_add_i32 m0, s87, 0x2000
	s_nop 0
	global_load_lds_dwordx4 v[222:223], off
	v_lshl_add_u64 v[222:223], s[62:63], 0, v[146:147]
	s_mov_b32 m0, s55
	s_nop 0
	global_load_lds_dwordx4 v[222:223], off
	s_mov_b32 m0, s68
	s_nop 0
	global_load_lds_dwordx4 v[224:225], off
	s_waitcnt vmcnt(8)
	s_waitcnt lgkmcnt(0)
	s_barrier
; #define PG8_STAGE(bufoff, gbase, voff) do { _Pragma("unroll") for (int _i = 0; _i < 2; ++_i) \
;         __builtin_amdgcn_global_load_lds((const unsigned*)((const char*)(gbase) + (voff)[_i]), (PG8_LAS unsigned*)(lds + (bufoff) + ldsw + _i * 8192), 16, 0, 0); } while (0)
; #define PG8_LDA(dst, b, h) do { _Pragma("unroll") for (int m = 0; m < 4; ++m) _Pragma("unroll") for (int k = 0; k < 2; ++k) dst[m][k] = *(const PG8_LAS bf16x8*)(lds + PG8_SA(b, h) + aoff + m * 2048 + k * 1024); } while (0)
; #define PG8_LDB(dst, b, h) do { _Pragma("unroll") for (int n = 0; n < 2; ++n) _Pragma("unroll") for (int k = 0; k < 2; ++k) dst[n][k] = *(const PG8_LAS bf16x8*)(lds + PG8_SB(b, h) + boff + n * 2048 + k * 1024); } while (0)
; #define PG8_MMA(ai, bj, At, Bt) do { __builtin_amdgcn_s_setprio(1); _Pragma("unroll") for (int m = 0; m < 4; ++m) _Pragma("unroll") for (int n = 0; n < 2; ++n) _Pragma("unroll") for (int k = 0; k < 2; ++k) \
;         acc[ai][bj][m][n] = __builtin_amdgcn_mfma_f32_16x16x32_bf16(Bt[n][k], At[m][k], acc[ai][bj][m][n], 0, 0, 0); __builtin_amdgcn_s_setprio(0); } while (0)
; #define PG8_WAIT_V(n) asm volatile("s_waitcnt vmcnt(" #n ")" ::: "memory")
; #define PG8_WAIT_L(n) asm volatile("s_waitcnt lgkmcnt(" #n ")" ::: "memory")
; #define PG8_BAR __builtin_amdgcn_s_barrier()
; #define PG8_SCHED __builtin_amdgcn_sched_barrier(0)
; template <class Epi, class Sched, bool ALIGN_EPI = false, bool SP2 = false>
; __device__ __forceinline__ void gemm_phase(PG8_LAS unsigned char* lds, const Gemm g, const Sched& S, const Epi& E) {
;     ...
;             PG8_WAIT_V(8); PG8_WAIT_L(0); PG8_BAR; PG8_MMA(1, 0, At, B0); PG8_MMA(1, 1, At, B1); PG8_BAR; PG8_SCHED;
;             PG8_LDB(B0, 1, 0); PG8_LDB(B1, 1, 1); PG8_SCHED; PG8_LDA(At, 1, 0); PG8_STAGE(PG8_SA(0, 1), a2 + hstep, voffA);
;             PG8_WAIT_V(8); PG8_WAIT_L(0); PG8_BAR; PG8_MMA(0, 0, At, B0); PG8_MMA(0, 1, At, B1); PG8_BAR; PG8_SCHED;
;             PG8_LDA(At, 1, 1); PG8_STAGE(PG8_SB(1, 0), b3, voffB); PG8_STAGE(PG8_SB(1, 1), b3 + hstep, voffB); PG8_STAGE(PG8_SA(1, 0), a3, voffA);
	s_waitcnt lgkmcnt(0)
	v_mfma_f32_16x16x32_bf16 v[62:65], v[98:101], v[188:191], v[62:65]
	v_mfma_f32_16x16x32_bf16 v[58:61], v[114:117], v[188:191], v[58:61]
	v_mfma_f32_16x16x32_bf16 v[46:49], v[98:101], v[196:199], v[46:49]
	v_mfma_f32_16x16x32_bf16 v[42:45], v[114:117], v[196:199], v[42:45]
	v_mfma_f32_16x16x32_bf16 v[30:33], v[98:101], v[204:207], v[30:33]
	v_mfma_f32_16x16x32_bf16 v[26:29], v[114:117], v[204:207], v[26:29]
	v_mfma_f32_16x16x32_bf16 v[14:17], v[98:101], v[212:215], v[14:17]
	v_mfma_f32_16x16x32_bf16 v[10:13], v[114:117], v[212:215], v[10:13]
	v_mfma_f32_16x16x32_bf16 v[62:65], v[106:109], v[192:195], v[62:65]
	v_mfma_f32_16x16x32_bf16 v[58:61], v[118:121], v[192:195], v[58:61]
	v_mfma_f32_16x16x32_bf16 v[46:49], v[106:109], v[200:203], v[46:49]
	v_mfma_f32_16x16x32_bf16 v[42:45], v[118:121], v[200:203], v[42:45]
	v_mfma_f32_16x16x32_bf16 v[30:33], v[106:109], v[208:211], v[30:33]
	v_mfma_f32_16x16x32_bf16 v[26:29], v[118:121], v[208:211], v[26:29]
	v_mfma_f32_16x16x32_bf16 v[14:17], v[106:109], v[216:219], v[14:17]
	v_mfma_f32_16x16x32_bf16 v[10:13], v[118:121], v[216:219], v[10:13]
	v_mfma_f32_16x16x32_bf16 v[54:57], v[164:167], v[188:191], v[54:57]
	v_mfma_f32_16x16x32_bf16 v[50:53], v[180:183], v[188:191], v[50:53]
	v_mfma_f32_16x16x32_bf16 v[38:41], v[164:167], v[196:199], v[38:41]
	v_mfma_f32_16x16x32_bf16 v[34:37], v[180:183], v[196:199], v[34:37]
	v_mfma_f32_16x16x32_bf16 v[22:25], v[164:167], v[204:207], v[22:25]
	v_mfma_f32_16x16x32_bf16 v[18:21], v[180:183], v[204:207], v[18:21]
	v_mfma_f32_16x16x32_bf16 v[6:9], v[164:167], v[212:215], v[6:9]
	v_mfma_f32_16x16x32_bf16 v[2:5], v[180:183], v[212:215], v[2:5]
	v_mfma_f32_16x16x32_bf16 v[54:57], v[176:179], v[192:195], v[54:57]
	v_mfma_f32_16x16x32_bf16 v[50:53], v[184:187], v[192:195], v[50:53]
	v_mfma_f32_16x16x32_bf16 v[38:41], v[176:179], v[200:203], v[38:41]
	v_mfma_f32_16x16x32_bf16 v[34:37], v[184:187], v[200:203], v[34:37]
	v_mfma_f32_16x16x32_bf16 v[22:25], v[176:179], v[208:211], v[22:25]
	v_mfma_f32_16x16x32_bf16 v[18:21], v[184:187], v[208:211], v[18:21]
	v_mfma_f32_16x16x32_bf16 v[6:9], v[176:179], v[216:219], v[6:9]
	v_mfma_f32_16x16x32_bf16 v[2:5], v[184:187], v[216:219], v[2:5]
	s_barrier
	s_add_i32 s87, 0, 0x18000
	s_add_i32 s88, 0, 0x1c000
	v_add_u32_e32 v118, s87, v170
	v_add_u32_e32 v154, s88, v170
	ds_read_b128 v[98:101], v118
	ds_read_b128 v[106:109], v118 offset:1024
	ds_read_b128 v[114:117], v118 offset:2048
	ds_read_b128 v[118:121], v118 offset:3072
	ds_read_b128 v[164:167], v154
	ds_read_b128 v[176:179], v154 offset:1024
	ds_read_b128 v[180:183], v154 offset:2048
	ds_read_b128 v[184:187], v154 offset:3072
	s_add_u32 s62, s62, 0x40000
	s_addc_u32 s63, s63, 0
	s_mov_b32 m0, s69
	v_lshl_add_u64 v[226:227], s[62:63], 0, v[146:147]
	ds_read_b128 v[188:191], v174 offset:32768
	ds_read_b128 v[192:195], v174 offset:33792
	ds_read_b128 v[196:199], v174 offset:34816
	ds_read_b128 v[200:203], v174 offset:35840
	ds_read_b128 v[204:207], v174 offset:36864
	ds_read_b128 v[208:211], v174 offset:37888
	ds_read_b128 v[212:215], v174 offset:38912
	ds_read_b128 v[216:219], v174 offset:39936
	global_load_lds_dwordx4 v[226:227], off
	v_lshl_add_u64 v[226:227], s[62:63], 0, v[150:151]
	s_mov_b32 m0, s70
	s_nop 0
	global_load_lds_dwordx4 v[226:227], off
	s_waitcnt vmcnt(8)
	s_waitcnt lgkmcnt(0)
	s_barrier
	s_waitcnt lgkmcnt(0)
	v_mfma_f32_16x16x32_bf16 v[142:145], v[98:101], v[188:191], v[142:145]
	v_mfma_f32_16x16x32_bf16 v[138:141], v[114:117], v[188:191], v[138:141]
	v_mfma_f32_16x16x32_bf16 v[126:129], v[98:101], v[196:199], v[126:129]
	v_mfma_f32_16x16x32_bf16 v[122:125], v[114:117], v[196:199], v[122:125]
	v_mfma_f32_16x16x32_bf16 v[94:97], v[98:101], v[204:207], v[94:97]
	v_mfma_f32_16x16x32_bf16 v[90:93], v[114:117], v[204:207], v[90:93]
	v_mfma_f32_16x16x32_bf16 v[78:81], v[98:101], v[212:215], v[78:81]
	v_mfma_f32_16x16x32_bf16 v[74:77], v[114:117], v[212:215], v[74:77]
	v_mfma_f32_16x16x32_bf16 v[142:145], v[106:109], v[192:195], v[142:145]
	v_mfma_f32_16x16x32_bf16 v[138:141], v[118:121], v[192:195], v[138:141]
	v_mfma_f32_16x16x32_bf16 v[126:129], v[106:109], v[200:203], v[126:129]
	v_mfma_f32_16x16x32_bf16 v[122:125], v[118:121], v[200:203], v[122:125]
	v_mfma_f32_16x16x32_bf16 v[94:97], v[106:109], v[208:211], v[94:97]
	v_mfma_f32_16x16x32_bf16 v[90:93], v[118:121], v[208:211], v[90:93]
	v_mfma_f32_16x16x32_bf16 v[78:81], v[106:109], v[216:219], v[78:81]
	v_mfma_f32_16x16x32_bf16 v[74:77], v[118:121], v[216:219], v[74:77]
	v_mfma_f32_16x16x32_bf16 v[134:137], v[164:167], v[188:191], v[134:137]
	v_mfma_f32_16x16x32_bf16 v[130:133], v[180:183], v[188:191], v[130:133]
	v_mfma_f32_16x16x32_bf16 v[110:113], v[164:167], v[196:199], v[110:113]
	v_mfma_f32_16x16x32_bf16 v[102:105], v[180:183], v[196:199], v[102:105]
	v_mfma_f32_16x16x32_bf16 v[86:89], v[164:167], v[204:207], v[86:89]
	v_mfma_f32_16x16x32_bf16 v[82:85], v[180:183], v[204:207], v[82:85]
	v_mfma_f32_16x16x32_bf16 v[70:73], v[164:167], v[212:215], v[70:73]
	v_mfma_f32_16x16x32_bf16 v[66:69], v[180:183], v[212:215], v[66:69]
	v_mfma_f32_16x16x32_bf16 v[134:137], v[176:179], v[192:195], v[134:137]
	v_mfma_f32_16x16x32_bf16 v[130:133], v[184:187], v[192:195], v[130:133]
	v_mfma_f32_16x16x32_bf16 v[110:113], v[176:179], v[200:203], v[110:113]
	v_mfma_f32_16x16x32_bf16 v[102:105], v[184:187], v[200:203], v[102:105]
	v_mfma_f32_16x16x32_bf16 v[86:89], v[176:179], v[208:211], v[86:89]
	v_mfma_f32_16x16x32_bf16 v[82:85], v[184:187], v[208:211], v[82:85]
	v_mfma_f32_16x16x32_bf16 v[70:73], v[176:179], v[216:219], v[70:73]
	v_mfma_f32_16x16x32_bf16 v[66:69], v[184:187], v[216:219], v[66:69]
	s_barrier
; #define PG8_STAGE(bufoff, gbase, voff) do { _Pragma("unroll") for (int _i = 0; _i < 2; ++_i) \
;         __builtin_amdgcn_global_load_lds((const unsigned*)((const char*)(gbase) + (voff)[_i]), (PG8_LAS unsigned*)(lds + (bufoff) + ldsw + _i * 8192), 16, 0, 0); } while (0)
; #define PG8_LDA(dst, b, h) do { _Pragma("unroll") for (int m = 0; m < 4; ++m) _Pragma("unroll") for (int k = 0; k < 2; ++k) dst[m][k] = *(const PG8_LAS bf16x8*)(lds + PG8_SA(b, h) + aoff + m * 2048 + k * 1024); } while (0)
; #define PG8_MMA(ai, bj, At, Bt) do { __builtin_amdgcn_s_setprio(1); _Pragma("unroll") for (int m = 0; m < 4; ++m) _Pragma("unroll") for (int n = 0; n < 2; ++n) _Pragma("unroll") for (int k = 0; k < 2; ++k) \
;         acc[ai][bj][m][n] = __builtin_amdgcn_mfma_f32_16x16x32_bf16(Bt[n][k], At[m][k], acc[ai][bj][m][n], 0, 0, 0); __builtin_amdgcn_s_setprio(0); } while (0)
; #define PG8_WAIT_V(n) asm volatile("s_waitcnt vmcnt(" #n ")" ::: "memory")
; #define PG8_WAIT_L(n) asm volatile("s_waitcnt lgkmcnt(" #n ")" ::: "memory")
; #define PG8_BAR __builtin_amdgcn_s_barrier()
; #define PG8_SCHED __builtin_amdgcn_sched_barrier(0)
; template <class Epi, class Sched, bool ALIGN_EPI = false, bool SP2 = false>
; __device__ __forceinline__ void gemm_phase(PG8_LAS unsigned char* lds, const Gemm g, const Sched& S, const Epi& E) {
;     ...
;         for (int t = 0; t < nt; t += 2) {
;     ...
;             PG8_LDA(At, 1, 1); PG8_STAGE(PG8_SB(1, 0), b3, voffB); PG8_STAGE(PG8_SB(1, 1), b3 + hstep, voffB); PG8_STAGE(PG8_SA(1, 0), a3, voffA);
;             PG8_WAIT_V(8); PG8_WAIT_L(0); PG8_BAR; PG8_MMA(1, 0, At, B0); PG8_MMA(1, 1, At, B1); PG8_BAR; PG8_SCHED;
	s_add_i32 s62, s87, s67
	v_lshl_add_u64 v[168:169], v[168:169], 0, s[12:13]
	s_mov_b32 m0, s62
	ds_read_b128 v[188:191], v174 offset:49152
	ds_read_b128 v[192:195], v174 offset:50176
	ds_read_b128 v[196:199], v174 offset:51200
	ds_read_b128 v[200:203], v174 offset:52224
	ds_read_b128 v[204:207], v174 offset:53248
	ds_read_b128 v[208:211], v174 offset:54272
	ds_read_b128 v[212:215], v174 offset:55296
	ds_read_b128 v[216:219], v174 offset:56320
	global_load_lds_dwordx4 v[168:169], off
	s_add_i32 m0, s62, 0x2000
	s_add_u32 s58, s58, 0x40080
	v_lshl_add_u64 v[168:169], v[220:221], 0, s[12:13]
	s_addc_u32 s59, s59, 0
	s_add_i32 s62, s88, s67
	global_load_lds_dwordx4 v[168:169], off
	v_lshl_add_u64 v[168:169], s[58:59], 0, v[148:149]
	s_mov_b32 m0, s62
	s_nop 0
	global_load_lds_dwordx4 v[168:169], off
	v_lshl_add_u64 v[168:169], s[58:59], 0, v[152:153]
	s_add_i32 m0, s62, 0x2000
	s_nop 0
	global_load_lds_dwordx4 v[168:169], off
	v_lshl_add_u64 v[168:169], v[222:223], 0, s[12:13]
	s_mov_b32 m0, s72
	s_nop 0
	global_load_lds_dwordx4 v[168:169], off
	v_lshl_add_u64 v[168:169], v[224:225], 0, s[12:13]
	s_mov_b32 m0, s73
	s_nop 0
	global_load_lds_dwordx4 v[168:169], off
	s_waitcnt vmcnt(8)
	s_waitcnt lgkmcnt(0)
	s_barrier
	s_waitcnt lgkmcnt(0)
	v_mfma_f32_16x16x32_bf16 v[62:65], v[98:101], v[188:191], v[62:65]
	v_mfma_f32_16x16x32_bf16 v[58:61], v[114:117], v[188:191], v[58:61]
	v_mfma_f32_16x16x32_bf16 v[46:49], v[98:101], v[196:199], v[46:49]
	v_mfma_f32_16x16x32_bf16 v[42:45], v[114:117], v[196:199], v[42:45]
	v_mfma_f32_16x16x32_bf16 v[30:33], v[98:101], v[204:207], v[30:33]
	v_mfma_f32_16x16x32_bf16 v[26:29], v[114:117], v[204:207], v[26:29]
	v_mfma_f32_16x16x32_bf16 v[14:17], v[98:101], v[212:215], v[14:17]
	v_mfma_f32_16x16x32_bf16 v[10:13], v[114:117], v[212:215], v[10:13]
	v_mfma_f32_16x16x32_bf16 v[62:65], v[106:109], v[192:195], v[62:65]
	v_mfma_f32_16x16x32_bf16 v[58:61], v[118:121], v[192:195], v[58:61]
	v_mfma_f32_16x16x32_bf16 v[46:49], v[106:109], v[200:203], v[46:49]
	v_mfma_f32_16x16x32_bf16 v[42:45], v[118:121], v[200:203], v[42:45]
	v_mfma_f32_16x16x32_bf16 v[30:33], v[106:109], v[208:211], v[30:33]
	v_mfma_f32_16x16x32_bf16 v[26:29], v[118:121], v[208:211], v[26:29]
	v_mfma_f32_16x16x32_bf16 v[14:17], v[106:109], v[216:219], v[14:17]
	v_mfma_f32_16x16x32_bf16 v[10:13], v[118:121], v[216:219], v[10:13]
	v_mfma_f32_16x16x32_bf16 v[54:57], v[164:167], v[188:191], v[54:57]
	v_mfma_f32_16x16x32_bf16 v[50:53], v[180:183], v[188:191], v[50:53]
	v_mfma_f32_16x16x32_bf16 v[38:41], v[164:167], v[196:199], v[38:41]
	v_mfma_f32_16x16x32_bf16 v[34:37], v[180:183], v[196:199], v[34:37]
	v_mfma_f32_16x16x32_bf16 v[22:25], v[164:167], v[204:207], v[22:25]
	v_mfma_f32_16x16x32_bf16 v[18:21], v[180:183], v[204:207], v[18:21]
	v_mfma_f32_16x16x32_bf16 v[6:9], v[164:167], v[212:215], v[6:9]
	v_mfma_f32_16x16x32_bf16 v[2:5], v[180:183], v[212:215], v[2:5]
	v_mfma_f32_16x16x32_bf16 v[54:57], v[176:179], v[192:195], v[54:57]
	v_mfma_f32_16x16x32_bf16 v[50:53], v[184:187], v[192:195], v[50:53]
	v_mfma_f32_16x16x32_bf16 v[38:41], v[176:179], v[200:203], v[38:41]
	v_mfma_f32_16x16x32_bf16 v[34:37], v[184:187], v[200:203], v[34:37]
	v_mfma_f32_16x16x32_bf16 v[22:25], v[176:179], v[208:211], v[22:25]
	v_mfma_f32_16x16x32_bf16 v[18:21], v[184:187], v[208:211], v[18:21]
	v_mfma_f32_16x16x32_bf16 v[6:9], v[176:179], v[216:219], v[6:9]
	v_mfma_f32_16x16x32_bf16 v[2:5], v[184:187], v[216:219], v[2:5]
	s_barrier
	s_add_i32 s86, s86, 2
	s_add_u32 s56, s56, 0x100
	s_addc_u32 s57, s57, 0
	s_add_u32 s84, s84, 0x100
	s_addc_u32 s85, s85, 0
	s_cmp_gt_u32 s86, 13
	s_cbranch_scc0 .LBB0_396
	s_and_b64 vcc, exec, s[14:15]
	s_cbranch_vccz .LBB0_399
	s_barrier

; #define PG8_STAGE(bufoff, gbase, voff) do { _Pragma("unroll") for (int _i = 0; _i < 2; ++_i) \
;         __builtin_amdgcn_global_load_lds((const unsigned*)((const char*)(gbase) + (voff)[_i]), (PG8_LAS unsigned*)(lds + (bufoff) + ldsw + _i * 8192), 16, 0, 0); } while (0)
; #define PG8_LDA(dst, b, h) do { _Pragma("unroll") for (int m = 0; m < 4; ++m) _Pragma("unroll") for (int k = 0; k < 2; ++k) dst[m][k] = *(const PG8_LAS bf16x8*)(lds + PG8_SA(b, h) + aoff + m * 2048 + k * 1024); } while (0)
; #define PG8_LDB(dst, b, h) do { _Pragma("unroll") for (int n = 0; n < 2; ++n) _Pragma("unroll") for (int k = 0; k < 2; ++k) dst[n][k] = *(const PG8_LAS bf16x8*)(lds + PG8_SB(b, h) + boff + n * 2048 + k * 1024); } while (0)
; #define PG8_MMA(ai, bj, At, Bt) do { __builtin_amdgcn_s_setprio(1); _Pragma("unroll") for (int m = 0; m < 4; ++m) _Pragma("unroll") for (int n = 0; n < 2; ++n) _Pragma("unroll") for (int k = 0; k < 2; ++k) \
;         acc[ai][bj][m][n] = __builtin_amdgcn_mfma_f32_16x16x32_bf16(Bt[n][k], At[m][k], acc[ai][bj][m][n], 0, 0, 0); __builtin_amdgcn_s_setprio(0); } while (0)
; #define PG8_WAIT_V(n) asm volatile("s_waitcnt vmcnt(" #n ")" ::: "memory")
; #define PG8_WAIT_L(n) asm volatile("s_waitcnt lgkmcnt(" #n ")" ::: "memory")
; #define PG8_BAR __builtin_amdgcn_s_barrier()
; template <class Epi, class Sched, bool ALIGN_EPI = false, bool SP2 = false>
; __device__ __forceinline__ void gemm_phase(PG8_LAS unsigned char* lds, const Gemm g, const Sched& S, const Epi& E) {
;     ...
;             const char* a1 = cA + (size_t)(t + 1) * kstep;
;             const char* a2 = last ? nA : cA + (size_t)(t + 2) * kstep; const char* b2 = last ? nB : cB + (size_t)(t + 2) * kstep;
;             const char* a3 = a2 + kstep; const char* b3 = b2 + kstep;
;             if (last && has_next) S.a_ready(nxt);
;             if constexpr (SP2) {
;             PG8_LDB(B0, 0, 0); PG8_LDB(B1, 0, 1); PG8_SCHED; PG8_LDA(At, 0, 0); PG8_STAGE(PG8_SA(1, 1), a1 + hstep, voffA);
;             PG8_WAIT_V(8); PG8_WAIT_L(0); PG8_BAR; PG8_MMA(0, 0, At, B0); PG8_MMA(0, 1, At, B1); PG8_BAR; PG8_SCHED;
;             PG8_LDA(At, 0, 1); PG8_STAGE(PG8_SB(0, 0), b2, voffB); PG8_STAGE(PG8_SB(0, 1), b2 + hstep, voffB); PG8_STAGE(PG8_SA(0, 0), a2, voffA);
;             PG8_WAIT_V(8); PG8_WAIT_L(0); PG8_BAR; PG8_MMA(1, 0, At, B0); PG8_MMA(1, 1, At, B1); PG8_BAR; PG8_SCHED;
.LBB0_475:
	v_add_u32_e32 v3, s82, v176
	ds_read_b128 v[134:137], v3
	ds_read_b128 v[138:141], v3 offset:1024
	ds_read_b128 v[142:145], v3 offset:2048
	ds_read_b128 v[146:149], v3 offset:3072
	v_add_u32_e32 v3, s83, v176
	s_add_u32 s64, s58, s62
	ds_read_b128 v[150:153], v3
	ds_read_b128 v[180:183], v3 offset:1024
	ds_read_b128 v[184:187], v3 offset:2048
	ds_read_b128 v[188:191], v3 offset:3072
	s_addc_u32 s65, s59, s63
	s_add_u32 s64, s64, 0x100
	s_addc_u32 s65, s65, 0
	s_add_u32 s93, s90, s62
	s_addc_u32 s94, s91, s63
	s_cmpk_eq_i32 s62, 0xf00
	s_cselect_b32 s67, s53, s65
	s_cselect_b32 s66, s84, s64
	s_cselect_b32 s65, s86, s94
	s_cselect_b32 s64, s87, s93
	v_lshl_add_u64 v[4:5], v[170:171], 0, s[62:63]
	s_add_i32 m0, s72, 0xc000
	ds_read_b128 v[192:195], v178
	ds_read_b128 v[196:199], v178 offset:1024
	ds_read_b128 v[200:203], v178 offset:2048
	ds_read_b128 v[204:207], v178 offset:3072
	ds_read_b128 v[208:211], v178 offset:4096
	ds_read_b128 v[212:215], v178 offset:5120
	ds_read_b128 v[216:219], v178 offset:6144
	ds_read_b128 v[220:223], v178 offset:7168
	global_load_lds_dwordx4 v[4:5], off
	v_lshl_add_u64 v[4:5], v[172:173], 0, s[62:63]
	s_add_i32 m0, s72, 0xe000
	s_nop 0
	global_load_lds_dwordx4 v[4:5], off
	s_waitcnt vmcnt(8)
	s_waitcnt lgkmcnt(0)
	s_barrier
	s_waitcnt lgkmcnt(0)
	v_mfma_f32_16x16x32_bf16 v[130:133], v[134:137], v[192:195], v[130:133]
	v_mfma_f32_16x16x32_bf16 v[126:129], v[142:145], v[192:195], v[126:129]
	v_mfma_f32_16x16x32_bf16 v[114:117], v[134:137], v[200:203], v[114:117]
	v_mfma_f32_16x16x32_bf16 v[110:113], v[142:145], v[200:203], v[110:113]
	v_mfma_f32_16x16x32_bf16 v[98:101], v[134:137], v[208:211], v[98:101]
	v_mfma_f32_16x16x32_bf16 v[94:97], v[142:145], v[208:211], v[94:97]
	v_mfma_f32_16x16x32_bf16 v[82:85], v[134:137], v[216:219], v[82:85]
	v_mfma_f32_16x16x32_bf16 v[78:81], v[142:145], v[216:219], v[78:81]
	v_mfma_f32_16x16x32_bf16 v[130:133], v[138:141], v[196:199], v[130:133]
	v_mfma_f32_16x16x32_bf16 v[126:129], v[146:149], v[196:199], v[126:129]
	v_mfma_f32_16x16x32_bf16 v[114:117], v[138:141], v[204:207], v[114:117]
	v_mfma_f32_16x16x32_bf16 v[110:113], v[146:149], v[204:207], v[110:113]
	v_mfma_f32_16x16x32_bf16 v[98:101], v[138:141], v[212:215], v[98:101]
	v_mfma_f32_16x16x32_bf16 v[94:97], v[146:149], v[212:215], v[94:97]
	v_mfma_f32_16x16x32_bf16 v[82:85], v[138:141], v[220:223], v[82:85]
	v_mfma_f32_16x16x32_bf16 v[78:81], v[146:149], v[220:223], v[78:81]
	v_mfma_f32_16x16x32_bf16 v[122:125], v[150:153], v[192:195], v[122:125]
	v_mfma_f32_16x16x32_bf16 v[118:121], v[184:187], v[192:195], v[118:121]
	v_mfma_f32_16x16x32_bf16 v[106:109], v[150:153], v[200:203], v[106:109]
	v_mfma_f32_16x16x32_bf16 v[102:105], v[184:187], v[200:203], v[102:105]
	v_mfma_f32_16x16x32_bf16 v[90:93], v[150:153], v[208:211], v[90:93]
	v_mfma_f32_16x16x32_bf16 v[86:89], v[184:187], v[208:211], v[86:89]
	v_mfma_f32_16x16x32_bf16 v[74:77], v[150:153], v[216:219], v[74:77]
	v_mfma_f32_16x16x32_bf16 v[70:73], v[184:187], v[216:219], v[70:73]
	v_mfma_f32_16x16x32_bf16 v[122:125], v[180:183], v[196:199], v[122:125]
	v_mfma_f32_16x16x32_bf16 v[118:121], v[188:191], v[196:199], v[118:121]
	v_mfma_f32_16x16x32_bf16 v[106:109], v[180:183], v[204:207], v[106:109]
	v_mfma_f32_16x16x32_bf16 v[102:105], v[188:191], v[204:207], v[102:105]
	v_mfma_f32_16x16x32_bf16 v[90:93], v[180:183], v[212:215], v[90:93]
	v_mfma_f32_16x16x32_bf16 v[86:89], v[188:191], v[212:215], v[86:89]
	v_mfma_f32_16x16x32_bf16 v[74:77], v[180:183], v[220:223], v[74:77]
	v_mfma_f32_16x16x32_bf16 v[70:73], v[188:191], v[220:223], v[70:73]
	s_barrier
	s_add_i32 s93, s82, s71
	v_lshl_add_u64 v[224:225], s[64:65], 0, v[156:157]
	s_mov_b32 m0, s93
	ds_read_b128 v[192:195], v178 offset:16384
	ds_read_b128 v[196:199], v178 offset:17408
	ds_read_b128 v[200:203], v178 offset:18432
	ds_read_b128 v[204:207], v178 offset:19456
	ds_read_b128 v[208:211], v178 offset:20480
	ds_read_b128 v[212:215], v178 offset:21504
	ds_read_b128 v[216:219], v178 offset:22528
	ds_read_b128 v[220:223], v178 offset:23552
	global_load_lds_dwordx4 v[224:225], off
	s_add_i32 m0, s93, 0x2000
	s_add_u32 s94, s64, 0x80000
	v_lshl_add_u64 v[226:227], s[64:65], 0, v[160:161]
	s_addc_u32 s95, s65, 0
	s_add_i32 s93, s83, s71
	global_load_lds_dwordx4 v[226:227], off
	v_lshl_add_u64 v[4:5], s[94:95], 0, v[156:157]
	s_mov_b32 m0, s93
	v_lshl_add_u64 v[228:229], s[66:67], 0, v[154:155]
	global_load_lds_dwordx4 v[4:5], off
	v_lshl_add_u64 v[4:5], s[94:95], 0, v[160:161]
	s_add_i32 m0, s93, 0x2000
	v_lshl_add_u64 v[230:231], s[66:67], 0, v[158:159]
	global_load_lds_dwordx4 v[4:5], off
	s_mov_b32 m0, s72
	s_nop 0
	global_load_lds_dwordx4 v[228:229], off
	s_mov_b32 m0, s73
	s_nop 0
	global_load_lds_dwordx4 v[230:231], off
	s_waitcnt vmcnt(8)
	s_waitcnt lgkmcnt(0)
	s_barrier
; #define PG8_STAGE(bufoff, gbase, voff) do { _Pragma("unroll") for (int _i = 0; _i < 2; ++_i) \
;         __builtin_amdgcn_global_load_lds((const unsigned*)((const char*)(gbase) + (voff)[_i]), (PG8_LAS unsigned*)(lds + (bufoff) + ldsw + _i * 8192), 16, 0, 0); } while (0)
; #define PG8_LDA(dst, b, h) do { _Pragma("unroll") for (int m = 0; m < 4; ++m) _Pragma("unroll") for (int k = 0; k < 2; ++k) dst[m][k] = *(const PG8_LAS bf16x8*)(lds + PG8_SA(b, h) + aoff + m * 2048 + k * 1024); } while (0)
; #define PG8_LDB(dst, b, h) do { _Pragma("unroll") for (int n = 0; n < 2; ++n) _Pragma("unroll") for (int k = 0; k < 2; ++k) dst[n][k] = *(const PG8_LAS bf16x8*)(lds + PG8_SB(b, h) + boff + n * 2048 + k * 1024); } while (0)
; #define PG8_MMA(ai, bj, At, Bt) do { __builtin_amdgcn_s_setprio(1); _Pragma("unroll") for (int m = 0; m < 4; ++m) _Pragma("unroll") for (int n = 0; n < 2; ++n) _Pragma("unroll") for (int k = 0; k < 2; ++k) \
;         acc[ai][bj][m][n] = __builtin_amdgcn_mfma_f32_16x16x32_bf16(Bt[n][k], At[m][k], acc[ai][bj][m][n], 0, 0, 0); __builtin_amdgcn_s_setprio(0); } while (0)
; #define PG8_WAIT_V(n) asm volatile("s_waitcnt vmcnt(" #n ")" ::: "memory")
; #define PG8_WAIT_L(n) asm volatile("s_waitcnt lgkmcnt(" #n ")" ::: "memory")
; #define PG8_BAR __builtin_amdgcn_s_barrier()
; #define PG8_SCHED __builtin_amdgcn_sched_barrier(0)
; template <class Epi, class Sched, bool ALIGN_EPI = false, bool SP2 = false>
; __device__ __forceinline__ void gemm_phase(PG8_LAS unsigned char* lds, const Gemm g, const Sched& S, const Epi& E) {
;     ...
;             PG8_WAIT_V(8); PG8_WAIT_L(0); PG8_BAR; PG8_MMA(1, 0, At, B0); PG8_MMA(1, 1, At, B1); PG8_BAR; PG8_SCHED;
;             PG8_LDB(B0, 1, 0); PG8_LDB(B1, 1, 1); PG8_SCHED; PG8_LDA(At, 1, 0); PG8_STAGE(PG8_SA(0, 1), a2 + hstep, voffA);
;             PG8_WAIT_V(8); PG8_WAIT_L(0); PG8_BAR; PG8_MMA(0, 0, At, B0); PG8_MMA(0, 1, At, B1); PG8_BAR; PG8_SCHED;
	s_waitcnt lgkmcnt(0)
	v_mfma_f32_16x16x32_bf16 v[66:69], v[134:137], v[192:195], v[66:69]
	v_mfma_f32_16x16x32_bf16 v[62:65], v[142:145], v[192:195], v[62:65]
	v_mfma_f32_16x16x32_bf16 v[50:53], v[134:137], v[200:203], v[50:53]
	v_mfma_f32_16x16x32_bf16 v[46:49], v[142:145], v[200:203], v[46:49]
	v_mfma_f32_16x16x32_bf16 v[34:37], v[134:137], v[208:211], v[34:37]
	v_mfma_f32_16x16x32_bf16 v[30:33], v[142:145], v[208:211], v[30:33]
	v_mfma_f32_16x16x32_bf16 v[18:21], v[134:137], v[216:219], v[18:21]
	v_mfma_f32_16x16x32_bf16 v[14:17], v[142:145], v[216:219], v[14:17]
	v_mfma_f32_16x16x32_bf16 v[66:69], v[138:141], v[196:199], v[66:69]
	v_mfma_f32_16x16x32_bf16 v[62:65], v[146:149], v[196:199], v[62:65]
	v_mfma_f32_16x16x32_bf16 v[50:53], v[138:141], v[204:207], v[50:53]
	v_mfma_f32_16x16x32_bf16 v[46:49], v[146:149], v[204:207], v[46:49]
	v_mfma_f32_16x16x32_bf16 v[34:37], v[138:141], v[212:215], v[34:37]
	v_mfma_f32_16x16x32_bf16 v[30:33], v[146:149], v[212:215], v[30:33]
	v_mfma_f32_16x16x32_bf16 v[18:21], v[138:141], v[220:223], v[18:21]
	v_mfma_f32_16x16x32_bf16 v[14:17], v[146:149], v[220:223], v[14:17]
	v_mfma_f32_16x16x32_bf16 v[58:61], v[150:153], v[192:195], v[58:61]
	v_mfma_f32_16x16x32_bf16 v[54:57], v[184:187], v[192:195], v[54:57]
	v_mfma_f32_16x16x32_bf16 v[42:45], v[150:153], v[200:203], v[42:45]
	v_mfma_f32_16x16x32_bf16 v[38:41], v[184:187], v[200:203], v[38:41]
	v_mfma_f32_16x16x32_bf16 v[26:29], v[150:153], v[208:211], v[26:29]
	v_mfma_f32_16x16x32_bf16 v[22:25], v[184:187], v[208:211], v[22:25]
	v_mfma_f32_16x16x32_bf16 v[10:13], v[150:153], v[216:219], v[10:13]
	v_mfma_f32_16x16x32_bf16 v[4:7], v[184:187], v[216:219], v[6:9]
	v_mfma_f32_16x16x32_bf16 v[58:61], v[180:183], v[196:199], v[58:61]
	v_mfma_f32_16x16x32_bf16 v[54:57], v[188:191], v[196:199], v[54:57]
	v_mfma_f32_16x16x32_bf16 v[42:45], v[180:183], v[204:207], v[42:45]
	v_mfma_f32_16x16x32_bf16 v[38:41], v[188:191], v[204:207], v[38:41]
	v_mfma_f32_16x16x32_bf16 v[26:29], v[180:183], v[212:215], v[26:29]
	v_mfma_f32_16x16x32_bf16 v[22:25], v[188:191], v[212:215], v[22:25]
	v_mfma_f32_16x16x32_bf16 v[10:13], v[180:183], v[220:223], v[10:13]
	v_mfma_f32_16x16x32_bf16 v[4:7], v[188:191], v[220:223], v[4:7]
	s_barrier
	s_add_i32 s93, 0, 0x18000
	v_add_u32_e32 v3, s93, v176
	s_add_i32 s94, 0, 0x1c000
	ds_read_b128 v[134:137], v3
	ds_read_b128 v[138:141], v3 offset:1024
	ds_read_b128 v[142:145], v3 offset:2048
	ds_read_b128 v[146:149], v3 offset:3072
	v_add_u32_e32 v3, s94, v176
	ds_read_b128 v[150:153], v3
	ds_read_b128 v[180:183], v3 offset:1024
	ds_read_b128 v[184:187], v3 offset:2048
	ds_read_b128 v[188:191], v3 offset:3072
	s_add_u32 s66, s66, 0x80000
	s_addc_u32 s67, s67, 0
	s_mov_b32 m0, s74
	v_lshl_add_u64 v[8:9], s[66:67], 0, v[154:155]
	ds_read_b128 v[192:195], v178 offset:32768
	ds_read_b128 v[196:199], v178 offset:33792
	ds_read_b128 v[200:203], v178 offset:34816
	ds_read_b128 v[204:207], v178 offset:35840
	ds_read_b128 v[208:211], v178 offset:36864
	ds_read_b128 v[212:215], v178 offset:37888
	ds_read_b128 v[216:219], v178 offset:38912
	ds_read_b128 v[220:223], v178 offset:39936
	global_load_lds_dwordx4 v[8:9], off
	v_lshl_add_u64 v[8:9], s[66:67], 0, v[158:159]
	s_mov_b32 m0, s75
	s_nop 0
	global_load_lds_dwordx4 v[8:9], off
	s_waitcnt vmcnt(8)
	s_waitcnt lgkmcnt(0)
	s_barrier
	s_waitcnt lgkmcnt(0)
	v_mfma_f32_16x16x32_bf16 v[130:133], v[134:137], v[192:195], v[130:133]
	v_mfma_f32_16x16x32_bf16 v[126:129], v[142:145], v[192:195], v[126:129]
	v_mfma_f32_16x16x32_bf16 v[114:117], v[134:137], v[200:203], v[114:117]
	v_mfma_f32_16x16x32_bf16 v[110:113], v[142:145], v[200:203], v[110:113]
	v_mfma_f32_16x16x32_bf16 v[98:101], v[134:137], v[208:211], v[98:101]
	v_mfma_f32_16x16x32_bf16 v[94:97], v[142:145], v[208:211], v[94:97]
	v_mfma_f32_16x16x32_bf16 v[82:85], v[134:137], v[216:219], v[82:85]
	v_mfma_f32_16x16x32_bf16 v[78:81], v[142:145], v[216:219], v[78:81]
	v_mfma_f32_16x16x32_bf16 v[130:133], v[138:141], v[196:199], v[130:133]
	v_mfma_f32_16x16x32_bf16 v[126:129], v[146:149], v[196:199], v[126:129]
	v_mfma_f32_16x16x32_bf16 v[114:117], v[138:141], v[204:207], v[114:117]
	v_mfma_f32_16x16x32_bf16 v[110:113], v[146:149], v[204:207], v[110:113]
	v_mfma_f32_16x16x32_bf16 v[98:101], v[138:141], v[212:215], v[98:101]
	v_mfma_f32_16x16x32_bf16 v[94:97], v[146:149], v[212:215], v[94:97]
	v_mfma_f32_16x16x32_bf16 v[82:85], v[138:141], v[220:223], v[82:85]
	v_mfma_f32_16x16x32_bf16 v[78:81], v[146:149], v[220:223], v[78:81]
	v_mfma_f32_16x16x32_bf16 v[122:125], v[150:153], v[192:195], v[122:125]
	v_mfma_f32_16x16x32_bf16 v[118:121], v[184:187], v[192:195], v[118:121]
	v_mfma_f32_16x16x32_bf16 v[106:109], v[150:153], v[200:203], v[106:109]
	v_mfma_f32_16x16x32_bf16 v[102:105], v[184:187], v[200:203], v[102:105]
	v_mfma_f32_16x16x32_bf16 v[90:93], v[150:153], v[208:211], v[90:93]
	v_mfma_f32_16x16x32_bf16 v[86:89], v[184:187], v[208:211], v[86:89]
	v_mfma_f32_16x16x32_bf16 v[74:77], v[150:153], v[216:219], v[74:77]
	v_mfma_f32_16x16x32_bf16 v[70:73], v[184:187], v[216:219], v[70:73]
	v_mfma_f32_16x16x32_bf16 v[122:125], v[180:183], v[196:199], v[122:125]
	v_mfma_f32_16x16x32_bf16 v[118:121], v[188:191], v[196:199], v[118:121]
	v_mfma_f32_16x16x32_bf16 v[106:109], v[180:183], v[204:207], v[106:109]
	v_mfma_f32_16x16x32_bf16 v[102:105], v[188:191], v[204:207], v[102:105]
	v_mfma_f32_16x16x32_bf16 v[90:93], v[180:183], v[212:215], v[90:93]
	v_mfma_f32_16x16x32_bf16 v[86:89], v[188:191], v[212:215], v[86:89]
	v_mfma_f32_16x16x32_bf16 v[74:77], v[180:183], v[220:223], v[74:77]
	v_mfma_f32_16x16x32_bf16 v[70:73], v[188:191], v[220:223], v[70:73]
	s_barrier
; #define PG8_STAGE(bufoff, gbase, voff) do { _Pragma("unroll") for (int _i = 0; _i < 2; ++_i) \
;         __builtin_amdgcn_global_load_lds((const unsigned*)((const char*)(gbase) + (voff)[_i]), (PG8_LAS unsigned*)(lds + (bufoff) + ldsw + _i * 8192), 16, 0, 0); } while (0)
; #define PG8_LDA(dst, b, h) do { _Pragma("unroll") for (int m = 0; m < 4; ++m) _Pragma("unroll") for (int k = 0; k < 2; ++k) dst[m][k] = *(const PG8_LAS bf16x8*)(lds + PG8_SA(b, h) + aoff + m * 2048 + k * 1024); } while (0)
; #define PG8_MMA(ai, bj, At, Bt) do { __builtin_amdgcn_s_setprio(1); _Pragma("unroll") for (int m = 0; m < 4; ++m) _Pragma("unroll") for (int n = 0; n < 2; ++n) _Pragma("unroll") for (int k = 0; k < 2; ++k) \
;         acc[ai][bj][m][n] = __builtin_amdgcn_mfma_f32_16x16x32_bf16(Bt[n][k], At[m][k], acc[ai][bj][m][n], 0, 0, 0); __builtin_amdgcn_s_setprio(0); } while (0)
; #define PG8_WAIT_V(n) asm volatile("s_waitcnt vmcnt(" #n ")" ::: "memory")
; #define PG8_WAIT_L(n) asm volatile("s_waitcnt lgkmcnt(" #n ")" ::: "memory")
; #define PG8_BAR __builtin_amdgcn_s_barrier()
; #define PG8_SCHED __builtin_amdgcn_sched_barrier(0)
; template <class Epi, class Sched, bool ALIGN_EPI = false, bool SP2 = false>
; __device__ __forceinline__ void gemm_phase(PG8_LAS unsigned char* lds, const Gemm g, const Sched& S, const Epi& E) {
;     ...
;         for (int t = 0; t < nt; t += 2) {
;             if constexpr (Epi::HAS_MID) { if (t == Epi::MID_T) E.mid(acc, cur, wr, wc, fr, fq); }
;             const bool last = (t == nt - 2);
;     ...
;             PG8_LDA(At, 1, 1); PG8_STAGE(PG8_SB(1, 0), b3, voffB); PG8_STAGE(PG8_SB(1, 1), b3 + hstep, voffB); PG8_STAGE(PG8_SA(1, 0), a3, voffA);
;             PG8_WAIT_V(8); PG8_WAIT_L(0); PG8_BAR; PG8_MMA(1, 0, At, B0); PG8_MMA(1, 1, At, B1); PG8_BAR; PG8_SCHED;
	s_add_i32 s66, s93, s71
	v_lshl_add_u64 v[8:9], v[224:225], 0, s[10:11]
	s_mov_b32 m0, s66
	ds_read_b128 v[192:195], v178 offset:49152
	ds_read_b128 v[196:199], v178 offset:50176
	ds_read_b128 v[200:203], v178 offset:51200
	ds_read_b128 v[204:207], v178 offset:52224
	ds_read_b128 v[208:211], v178 offset:53248
	ds_read_b128 v[212:215], v178 offset:54272
	ds_read_b128 v[216:219], v178 offset:55296
	ds_read_b128 v[220:223], v178 offset:56320
	global_load_lds_dwordx4 v[8:9], off
	s_add_i32 m0, s66, 0x2000
	s_add_u32 s64, s64, 0x80080
	v_lshl_add_u64 v[8:9], v[226:227], 0, s[10:11]
	s_addc_u32 s65, s65, 0
	s_add_i32 s66, s94, s71
	global_load_lds_dwordx4 v[8:9], off
	v_lshl_add_u64 v[8:9], s[64:65], 0, v[156:157]
	s_mov_b32 m0, s66
	s_nop 0
	global_load_lds_dwordx4 v[8:9], off
	v_lshl_add_u64 v[8:9], s[64:65], 0, v[160:161]
	s_add_i32 m0, s66, 0x2000
	s_nop 0
	global_load_lds_dwordx4 v[8:9], off
	v_lshl_add_u64 v[8:9], v[228:229], 0, s[10:11]
	s_mov_b32 m0, s79
	s_nop 0
	global_load_lds_dwordx4 v[8:9], off
	v_lshl_add_u64 v[8:9], v[230:231], 0, s[10:11]
	s_mov_b32 m0, s80
	s_nop 0
	global_load_lds_dwordx4 v[8:9], off
	s_waitcnt vmcnt(8)
	s_waitcnt lgkmcnt(0)
	s_barrier
	s_waitcnt lgkmcnt(0)
	v_mfma_f32_16x16x32_bf16 v[66:69], v[134:137], v[192:195], v[66:69]
	v_mfma_f32_16x16x32_bf16 v[62:65], v[142:145], v[192:195], v[62:65]
	v_mfma_f32_16x16x32_bf16 v[50:53], v[134:137], v[200:203], v[50:53]
	v_mfma_f32_16x16x32_bf16 v[46:49], v[142:145], v[200:203], v[46:49]
	v_mfma_f32_16x16x32_bf16 v[34:37], v[134:137], v[208:211], v[34:37]
	v_mfma_f32_16x16x32_bf16 v[30:33], v[142:145], v[208:211], v[30:33]
	v_mfma_f32_16x16x32_bf16 v[18:21], v[134:137], v[216:219], v[18:21]
	v_mfma_f32_16x16x32_bf16 v[14:17], v[142:145], v[216:219], v[14:17]
	v_mfma_f32_16x16x32_bf16 v[66:69], v[138:141], v[196:199], v[66:69]
	v_mfma_f32_16x16x32_bf16 v[62:65], v[146:149], v[196:199], v[62:65]
	v_mfma_f32_16x16x32_bf16 v[50:53], v[138:141], v[204:207], v[50:53]
	v_mfma_f32_16x16x32_bf16 v[46:49], v[146:149], v[204:207], v[46:49]
	v_mfma_f32_16x16x32_bf16 v[34:37], v[138:141], v[212:215], v[34:37]
	v_mfma_f32_16x16x32_bf16 v[30:33], v[146:149], v[212:215], v[30:33]
	v_mfma_f32_16x16x32_bf16 v[18:21], v[138:141], v[220:223], v[18:21]
	v_mfma_f32_16x16x32_bf16 v[14:17], v[146:149], v[220:223], v[14:17]
	v_mfma_f32_16x16x32_bf16 v[58:61], v[150:153], v[192:195], v[58:61]
	v_mfma_f32_16x16x32_bf16 v[54:57], v[184:187], v[192:195], v[54:57]
	v_mfma_f32_16x16x32_bf16 v[42:45], v[150:153], v[200:203], v[42:45]
	v_mfma_f32_16x16x32_bf16 v[38:41], v[184:187], v[200:203], v[38:41]
	v_mfma_f32_16x16x32_bf16 v[26:29], v[150:153], v[208:211], v[26:29]
	v_mfma_f32_16x16x32_bf16 v[22:25], v[184:187], v[208:211], v[22:25]
	v_mfma_f32_16x16x32_bf16 v[8:11], v[150:153], v[216:219], v[10:13]
	v_mfma_f32_16x16x32_bf16 v[4:7], v[184:187], v[216:219], v[4:7]
	v_mfma_f32_16x16x32_bf16 v[58:61], v[180:183], v[196:199], v[58:61]
	v_mfma_f32_16x16x32_bf16 v[54:57], v[188:191], v[196:199], v[54:57]
	v_mfma_f32_16x16x32_bf16 v[42:45], v[180:183], v[204:207], v[42:45]
	v_mfma_f32_16x16x32_bf16 v[38:41], v[188:191], v[204:207], v[38:41]
	v_mfma_f32_16x16x32_bf16 v[26:29], v[180:183], v[212:215], v[26:29]
	v_mfma_f32_16x16x32_bf16 v[22:25], v[188:191], v[212:215], v[22:25]
	v_mfma_f32_16x16x32_bf16 v[10:13], v[180:183], v[220:223], v[8:11]
	v_mfma_f32_16x16x32_bf16 v[6:9], v[188:191], v[220:223], v[4:7]
	s_barrier
	s_add_i32 s92, s92, 2
	s_add_u32 s62, s62, 0x100
	s_addc_u32 s63, s63, 0
	s_cmp_gt_u32 s92, 29
	s_cbranch_scc1 .LBB0_478

; #define PG8_STAGE(bufoff, gbase, voff) do { _Pragma("unroll") for (int _i = 0; _i < 2; ++_i) \
;         __builtin_amdgcn_global_load_lds((const unsigned*)((const char*)(gbase) + (voff)[_i]), (PG8_LAS unsigned*)(lds + (bufoff) + ldsw + _i * 8192), 16, 0, 0); } while (0)
; #define PG8_LDA(dst, b, h) do { _Pragma("unroll") for (int m = 0; m < 4; ++m) _Pragma("unroll") for (int k = 0; k < 2; ++k) dst[m][k] = *(const PG8_LAS bf16x8*)(lds + PG8_SA(b, h) + aoff + m * 2048 + k * 1024); } while (0)
; #define PG8_LDB(dst, b, h) do { _Pragma("unroll") for (int n = 0; n < 2; ++n) _Pragma("unroll") for (int k = 0; k < 2; ++k) dst[n][k] = *(const PG8_LAS bf16x8*)(lds + PG8_SB(b, h) + boff + n * 2048 + k * 1024); } while (0)
; #define PG8_MMA(ai, bj, At, Bt) do { __builtin_amdgcn_s_setprio(1); _Pragma("unroll") for (int m = 0; m < 4; ++m) _Pragma("unroll") for (int n = 0; n < 2; ++n) _Pragma("unroll") for (int k = 0; k < 2; ++k) \
;         acc[ai][bj][m][n] = __builtin_amdgcn_mfma_f32_16x16x32_bf16(Bt[n][k], At[m][k], acc[ai][bj][m][n], 0, 0, 0); __builtin_amdgcn_s_setprio(0); } while (0)
; #define PG8_WAIT_V(n) asm volatile("s_waitcnt vmcnt(" #n ")" ::: "memory")
; #define PG8_WAIT_L(n) asm volatile("s_waitcnt lgkmcnt(" #n ")" ::: "memory")
; #define PG8_BAR __builtin_amdgcn_s_barrier()
; template <class Epi, class Sched, bool ALIGN_EPI = false, bool SP2 = false>
; __device__ __forceinline__ void gemm_phase(PG8_LAS unsigned char* lds, const Gemm g, const Sched& S, const Epi& E) {
;     ...
;             const char* a1 = cA + (size_t)(t + 1) * kstep;
;             const char* a2 = last ? nA : cA + (size_t)(t + 2) * kstep; const char* b2 = last ? nB : cB + (size_t)(t + 2) * kstep;
;             const char* a3 = a2 + kstep; const char* b3 = b2 + kstep;
;             if (last && has_next) S.a_ready(nxt);
;             if constexpr (SP2) {
;             PG8_LDB(B0, 0, 0); PG8_LDB(B1, 0, 1); PG8_SCHED; PG8_LDA(At, 0, 0); PG8_STAGE(PG8_SA(1, 1), a1 + hstep, voffA);
;             PG8_WAIT_V(8); PG8_WAIT_L(0); PG8_BAR; PG8_MMA(0, 0, At, B0); PG8_MMA(0, 1, At, B1); PG8_BAR; PG8_SCHED;
;             PG8_LDA(At, 0, 1); PG8_STAGE(PG8_SB(0, 0), b2, voffB); PG8_STAGE(PG8_SB(0, 1), b2 + hstep, voffB); PG8_STAGE(PG8_SA(0, 0), a2, voffA);
;             PG8_WAIT_V(8); PG8_WAIT_L(0); PG8_BAR; PG8_MMA(1, 0, At, B0); PG8_MMA(1, 1, At, B1); PG8_BAR; PG8_SCHED;
.LBB0_558:
	ds_read_b128 v[140:143], v181
	ds_read_b128 v[144:147], v181 offset:1024
	ds_read_b128 v[148:151], v181 offset:2048
	ds_read_b128 v[152:155], v181 offset:3072
	ds_read_b128 v[156:159], v182
	ds_read_b128 v[160:163], v182 offset:1024
	ds_read_b128 v[164:167], v182 offset:2048
	ds_read_b128 v[168:171], v182 offset:3072
	s_add_u32 s48, s46, 0xfffc0080
	s_addc_u32 s49, s47, -1
	s_cmp_eq_u32 s70, 12
	s_cselect_b32 s51, s9, s49
	s_cselect_b32 s50, s39, s48
	s_cselect_b32 s49, s31, s69
	s_cselect_b32 s48, s45, s68
	v_lshl_add_u64 v[176:177], s[46:47], 0, v[132:133]
	s_add_i32 m0, s54, 0xc000
	ds_read_b128 v[172:175], v183
	ds_read_b128 v[188:191], v183 offset:1024
	ds_read_b128 v[192:195], v183 offset:2048
	ds_read_b128 v[196:199], v183 offset:3072
	ds_read_b128 v[200:203], v183 offset:4096
	ds_read_b128 v[204:207], v183 offset:5120
	ds_read_b128 v[208:211], v183 offset:6144
	ds_read_b128 v[212:215], v183 offset:7168
	global_load_lds_dwordx4 v[176:177], off
	v_lshl_add_u64 v[176:177], s[46:47], 0, v[134:135]
	s_add_i32 m0, s54, 0xe000
	s_nop 0
	global_load_lds_dwordx4 v[176:177], off
	s_waitcnt vmcnt(8)
	s_waitcnt lgkmcnt(0)
	s_barrier
	s_waitcnt lgkmcnt(0)
	v_mfma_f32_16x16x32_bf16 v[124:127], v[140:143], v[172:175], v[124:127]
	v_mfma_f32_16x16x32_bf16 v[120:123], v[148:151], v[172:175], v[120:123]
	v_mfma_f32_16x16x32_bf16 v[108:111], v[140:143], v[192:195], v[108:111]
	v_mfma_f32_16x16x32_bf16 v[104:107], v[148:151], v[192:195], v[104:107]
	v_mfma_f32_16x16x32_bf16 v[92:95], v[140:143], v[200:203], v[92:95]
	v_mfma_f32_16x16x32_bf16 v[88:91], v[148:151], v[200:203], v[88:91]
	v_mfma_f32_16x16x32_bf16 v[76:79], v[140:143], v[208:211], v[76:79]
	v_mfma_f32_16x16x32_bf16 v[72:75], v[148:151], v[208:211], v[72:75]
	v_mfma_f32_16x16x32_bf16 v[124:127], v[144:147], v[188:191], v[124:127]
	v_mfma_f32_16x16x32_bf16 v[120:123], v[152:155], v[188:191], v[120:123]
	v_mfma_f32_16x16x32_bf16 v[108:111], v[144:147], v[196:199], v[108:111]
	v_mfma_f32_16x16x32_bf16 v[104:107], v[152:155], v[196:199], v[104:107]
	v_mfma_f32_16x16x32_bf16 v[92:95], v[144:147], v[204:207], v[92:95]
	v_mfma_f32_16x16x32_bf16 v[88:91], v[152:155], v[204:207], v[88:91]
	v_mfma_f32_16x16x32_bf16 v[76:79], v[144:147], v[212:215], v[76:79]
	v_mfma_f32_16x16x32_bf16 v[72:75], v[152:155], v[212:215], v[72:75]
	v_mfma_f32_16x16x32_bf16 v[116:119], v[156:159], v[172:175], v[116:119]
	v_mfma_f32_16x16x32_bf16 v[112:115], v[164:167], v[172:175], v[112:115]
	v_mfma_f32_16x16x32_bf16 v[100:103], v[156:159], v[192:195], v[100:103]
	v_mfma_f32_16x16x32_bf16 v[96:99], v[164:167], v[192:195], v[96:99]
	v_mfma_f32_16x16x32_bf16 v[84:87], v[156:159], v[200:203], v[84:87]
	v_mfma_f32_16x16x32_bf16 v[80:83], v[164:167], v[200:203], v[80:83]
	v_mfma_f32_16x16x32_bf16 v[68:71], v[156:159], v[208:211], v[68:71]
	v_mfma_f32_16x16x32_bf16 v[64:67], v[164:167], v[208:211], v[64:67]
	v_mfma_f32_16x16x32_bf16 v[116:119], v[160:163], v[188:191], v[116:119]
	v_mfma_f32_16x16x32_bf16 v[112:115], v[168:171], v[188:191], v[112:115]
	v_mfma_f32_16x16x32_bf16 v[100:103], v[160:163], v[196:199], v[100:103]
	v_mfma_f32_16x16x32_bf16 v[96:99], v[168:171], v[196:199], v[96:99]
	v_mfma_f32_16x16x32_bf16 v[84:87], v[160:163], v[204:207], v[84:87]
	v_mfma_f32_16x16x32_bf16 v[80:83], v[168:171], v[204:207], v[80:83]
	v_mfma_f32_16x16x32_bf16 v[68:71], v[160:163], v[212:215], v[68:71]
	v_mfma_f32_16x16x32_bf16 v[64:67], v[168:171], v[212:215], v[64:67]
	s_barrier
	s_add_i32 s71, s65, s53
	v_lshl_add_u64 v[176:177], s[48:49], 0, v[128:129]
	s_mov_b32 m0, s71
	ds_read_b128 v[172:175], v183 offset:16384
	ds_read_b128 v[188:191], v183 offset:17408
	ds_read_b128 v[192:195], v183 offset:18432
	ds_read_b128 v[196:199], v183 offset:19456
	ds_read_b128 v[200:203], v183 offset:20480
	ds_read_b128 v[204:207], v183 offset:21504
	ds_read_b128 v[208:211], v183 offset:22528
	ds_read_b128 v[212:215], v183 offset:23552
	global_load_lds_dwordx4 v[176:177], off
	s_add_i32 m0, s71, 0x2000
	s_add_u32 s72, s48, 0x40000
	v_lshl_add_u64 v[216:217], s[48:49], 0, v[130:131]
	s_addc_u32 s73, s49, 0
	s_add_i32 s71, s66, s53
	global_load_lds_dwordx4 v[216:217], off
	v_lshl_add_u64 v[218:219], s[72:73], 0, v[128:129]
	s_mov_b32 m0, s71
	v_lshl_add_u64 v[220:221], s[50:51], 0, v[130:131]
	global_load_lds_dwordx4 v[218:219], off
	v_lshl_add_u64 v[218:219], s[72:73], 0, v[130:131]
	s_add_i32 m0, s71, 0x2000
	s_nop 0
	global_load_lds_dwordx4 v[218:219], off
	v_lshl_add_u64 v[218:219], s[50:51], 0, v[128:129]
	s_mov_b32 m0, s54
	s_nop 0
	global_load_lds_dwordx4 v[218:219], off
	s_mov_b32 m0, s55
	s_nop 0
	global_load_lds_dwordx4 v[220:221], off
	s_waitcnt vmcnt(8)
	s_waitcnt lgkmcnt(0)
	s_barrier
; #define PG8_STAGE(bufoff, gbase, voff) do { _Pragma("unroll") for (int _i = 0; _i < 2; ++_i) \
;         __builtin_amdgcn_global_load_lds((const unsigned*)((const char*)(gbase) + (voff)[_i]), (PG8_LAS unsigned*)(lds + (bufoff) + ldsw + _i * 8192), 16, 0, 0); } while (0)
; #define PG8_LDA(dst, b, h) do { _Pragma("unroll") for (int m = 0; m < 4; ++m) _Pragma("unroll") for (int k = 0; k < 2; ++k) dst[m][k] = *(const PG8_LAS bf16x8*)(lds + PG8_SA(b, h) + aoff + m * 2048 + k * 1024); } while (0)
; #define PG8_LDB(dst, b, h) do { _Pragma("unroll") for (int n = 0; n < 2; ++n) _Pragma("unroll") for (int k = 0; k < 2; ++k) dst[n][k] = *(const PG8_LAS bf16x8*)(lds + PG8_SB(b, h) + boff + n * 2048 + k * 1024); } while (0)
; #define PG8_MMA(ai, bj, At, Bt) do { __builtin_amdgcn_s_setprio(1); _Pragma("unroll") for (int m = 0; m < 4; ++m) _Pragma("unroll") for (int n = 0; n < 2; ++n) _Pragma("unroll") for (int k = 0; k < 2; ++k) \
;         acc[ai][bj][m][n] = __builtin_amdgcn_mfma_f32_16x16x32_bf16(Bt[n][k], At[m][k], acc[ai][bj][m][n], 0, 0, 0); __builtin_amdgcn_s_setprio(0); } while (0)
; #define PG8_WAIT_V(n) asm volatile("s_waitcnt vmcnt(" #n ")" ::: "memory")
; #define PG8_WAIT_L(n) asm volatile("s_waitcnt lgkmcnt(" #n ")" ::: "memory")
; #define PG8_BAR __builtin_amdgcn_s_barrier()
; #define PG8_SCHED __builtin_amdgcn_sched_barrier(0)
; template <class Epi, class Sched, bool ALIGN_EPI = false, bool SP2 = false>
; __device__ __forceinline__ void gemm_phase(PG8_LAS unsigned char* lds, const Gemm g, const Sched& S, const Epi& E) {
;     ...
;             PG8_WAIT_V(8); PG8_WAIT_L(0); PG8_BAR; PG8_MMA(1, 0, At, B0); PG8_MMA(1, 1, At, B1); PG8_BAR; PG8_SCHED;
;             PG8_LDB(B0, 1, 0); PG8_LDB(B1, 1, 1); PG8_SCHED; PG8_LDA(At, 1, 0); PG8_STAGE(PG8_SA(0, 1), a2 + hstep, voffA);
;             PG8_WAIT_V(8); PG8_WAIT_L(0); PG8_BAR; PG8_MMA(0, 0, At, B0); PG8_MMA(0, 1, At, B1); PG8_BAR; PG8_SCHED;
	s_waitcnt lgkmcnt(0)
	v_mfma_f32_16x16x32_bf16 v[60:63], v[140:143], v[172:175], v[60:63]
	v_mfma_f32_16x16x32_bf16 v[56:59], v[148:151], v[172:175], v[56:59]
	v_mfma_f32_16x16x32_bf16 v[44:47], v[140:143], v[192:195], v[44:47]
	v_mfma_f32_16x16x32_bf16 v[40:43], v[148:151], v[192:195], v[40:43]
	v_mfma_f32_16x16x32_bf16 v[28:31], v[140:143], v[200:203], v[28:31]
	v_mfma_f32_16x16x32_bf16 v[24:27], v[148:151], v[200:203], v[24:27]
	v_mfma_f32_16x16x32_bf16 v[12:15], v[140:143], v[208:211], v[12:15]
	v_mfma_f32_16x16x32_bf16 v[8:11], v[148:151], v[208:211], v[8:11]
	v_mfma_f32_16x16x32_bf16 v[60:63], v[144:147], v[188:191], v[60:63]
	v_mfma_f32_16x16x32_bf16 v[56:59], v[152:155], v[188:191], v[56:59]
	v_mfma_f32_16x16x32_bf16 v[44:47], v[144:147], v[196:199], v[44:47]
	v_mfma_f32_16x16x32_bf16 v[40:43], v[152:155], v[196:199], v[40:43]
	v_mfma_f32_16x16x32_bf16 v[28:31], v[144:147], v[204:207], v[28:31]
	v_mfma_f32_16x16x32_bf16 v[24:27], v[152:155], v[204:207], v[24:27]
	v_mfma_f32_16x16x32_bf16 v[12:15], v[144:147], v[212:215], v[12:15]
	v_mfma_f32_16x16x32_bf16 v[8:11], v[152:155], v[212:215], v[8:11]
	v_mfma_f32_16x16x32_bf16 v[52:55], v[156:159], v[172:175], v[52:55]
	v_mfma_f32_16x16x32_bf16 v[48:51], v[164:167], v[172:175], v[48:51]
	v_mfma_f32_16x16x32_bf16 v[36:39], v[156:159], v[192:195], v[36:39]
	v_mfma_f32_16x16x32_bf16 v[32:35], v[164:167], v[192:195], v[32:35]
	v_mfma_f32_16x16x32_bf16 v[20:23], v[156:159], v[200:203], v[20:23]
	v_mfma_f32_16x16x32_bf16 v[16:19], v[164:167], v[200:203], v[16:19]
	v_mfma_f32_16x16x32_bf16 v[4:7], v[156:159], v[208:211], v[4:7]
	v_mfma_f32_16x16x32_bf16 v[0:3], v[164:167], v[208:211], v[0:3]
	v_mfma_f32_16x16x32_bf16 v[52:55], v[160:163], v[188:191], v[52:55]
	v_mfma_f32_16x16x32_bf16 v[48:51], v[168:171], v[188:191], v[48:51]
	v_mfma_f32_16x16x32_bf16 v[36:39], v[160:163], v[196:199], v[36:39]
	v_mfma_f32_16x16x32_bf16 v[32:35], v[168:171], v[196:199], v[32:35]
	v_mfma_f32_16x16x32_bf16 v[20:23], v[160:163], v[204:207], v[20:23]
	v_mfma_f32_16x16x32_bf16 v[16:19], v[168:171], v[204:207], v[16:19]
	v_mfma_f32_16x16x32_bf16 v[4:7], v[160:163], v[212:215], v[4:7]
	v_mfma_f32_16x16x32_bf16 v[0:3], v[168:171], v[212:215], v[0:3]
	s_barrier
	s_add_i32 s71, 0, 0x18000
	s_add_i32 s72, 0, 0x1c000
	v_add_u32_e32 v152, s71, v179
	v_add_u32_e32 v168, s72, v179
	ds_read_b128 v[140:143], v152
	ds_read_b128 v[144:147], v152 offset:1024
	ds_read_b128 v[148:151], v152 offset:2048
	ds_read_b128 v[152:155], v152 offset:3072
	ds_read_b128 v[156:159], v168
	ds_read_b128 v[160:163], v168 offset:1024
	ds_read_b128 v[164:167], v168 offset:2048
	ds_read_b128 v[168:171], v168 offset:3072
	s_add_u32 s50, s50, 0x40000
	s_addc_u32 s51, s51, 0
	s_mov_b32 m0, s56
	v_lshl_add_u64 v[222:223], s[50:51], 0, v[128:129]
	ds_read_b128 v[172:175], v183 offset:32768
	ds_read_b128 v[188:191], v183 offset:33792
	ds_read_b128 v[192:195], v183 offset:34816
	ds_read_b128 v[196:199], v183 offset:35840
	ds_read_b128 v[200:203], v183 offset:36864
	ds_read_b128 v[204:207], v183 offset:37888
	ds_read_b128 v[208:211], v183 offset:38912
	ds_read_b128 v[212:215], v183 offset:39936
	global_load_lds_dwordx4 v[222:223], off
	v_lshl_add_u64 v[222:223], s[50:51], 0, v[130:131]
	s_mov_b32 m0, s57
	s_nop 0
	global_load_lds_dwordx4 v[222:223], off
	s_waitcnt vmcnt(8)
	s_waitcnt lgkmcnt(0)
	s_barrier
	s_waitcnt lgkmcnt(0)
	v_mfma_f32_16x16x32_bf16 v[124:127], v[140:143], v[172:175], v[124:127]
	v_mfma_f32_16x16x32_bf16 v[120:123], v[148:151], v[172:175], v[120:123]
	v_mfma_f32_16x16x32_bf16 v[108:111], v[140:143], v[192:195], v[108:111]
	v_mfma_f32_16x16x32_bf16 v[104:107], v[148:151], v[192:195], v[104:107]
	v_mfma_f32_16x16x32_bf16 v[92:95], v[140:143], v[200:203], v[92:95]
	v_mfma_f32_16x16x32_bf16 v[88:91], v[148:151], v[200:203], v[88:91]
	v_mfma_f32_16x16x32_bf16 v[76:79], v[140:143], v[208:211], v[76:79]
	v_mfma_f32_16x16x32_bf16 v[72:75], v[148:151], v[208:211], v[72:75]
	v_mfma_f32_16x16x32_bf16 v[124:127], v[144:147], v[188:191], v[124:127]
	v_mfma_f32_16x16x32_bf16 v[120:123], v[152:155], v[188:191], v[120:123]
	v_mfma_f32_16x16x32_bf16 v[108:111], v[144:147], v[196:199], v[108:111]
	v_mfma_f32_16x16x32_bf16 v[104:107], v[152:155], v[196:199], v[104:107]
	v_mfma_f32_16x16x32_bf16 v[92:95], v[144:147], v[204:207], v[92:95]
	v_mfma_f32_16x16x32_bf16 v[88:91], v[152:155], v[204:207], v[88:91]
	v_mfma_f32_16x16x32_bf16 v[76:79], v[144:147], v[212:215], v[76:79]
	v_mfma_f32_16x16x32_bf16 v[72:75], v[152:155], v[212:215], v[72:75]
	v_mfma_f32_16x16x32_bf16 v[116:119], v[156:159], v[172:175], v[116:119]
	v_mfma_f32_16x16x32_bf16 v[112:115], v[164:167], v[172:175], v[112:115]
	v_mfma_f32_16x16x32_bf16 v[100:103], v[156:159], v[192:195], v[100:103]
	v_mfma_f32_16x16x32_bf16 v[96:99], v[164:167], v[192:195], v[96:99]
	v_mfma_f32_16x16x32_bf16 v[84:87], v[156:159], v[200:203], v[84:87]
	v_mfma_f32_16x16x32_bf16 v[80:83], v[164:167], v[200:203], v[80:83]
	v_mfma_f32_16x16x32_bf16 v[68:71], v[156:159], v[208:211], v[68:71]
	v_mfma_f32_16x16x32_bf16 v[64:67], v[164:167], v[208:211], v[64:67]
	v_mfma_f32_16x16x32_bf16 v[116:119], v[160:163], v[188:191], v[116:119]
	v_mfma_f32_16x16x32_bf16 v[112:115], v[168:171], v[188:191], v[112:115]
	v_mfma_f32_16x16x32_bf16 v[100:103], v[160:163], v[196:199], v[100:103]
	v_mfma_f32_16x16x32_bf16 v[96:99], v[168:171], v[196:199], v[96:99]
	v_mfma_f32_16x16x32_bf16 v[84:87], v[160:163], v[204:207], v[84:87]
	v_mfma_f32_16x16x32_bf16 v[80:83], v[168:171], v[204:207], v[80:83]
	v_mfma_f32_16x16x32_bf16 v[68:71], v[160:163], v[212:215], v[68:71]
	v_mfma_f32_16x16x32_bf16 v[64:67], v[168:171], v[212:215], v[64:67]
	s_barrier
; #define PG8_STAGE(bufoff, gbase, voff) do { _Pragma("unroll") for (int _i = 0; _i < 2; ++_i) \
;         __builtin_amdgcn_global_load_lds((const unsigned*)((const char*)(gbase) + (voff)[_i]), (PG8_LAS unsigned*)(lds + (bufoff) + ldsw + _i * 8192), 16, 0, 0); } while (0)
; #define PG8_LDA(dst, b, h) do { _Pragma("unroll") for (int m = 0; m < 4; ++m) _Pragma("unroll") for (int k = 0; k < 2; ++k) dst[m][k] = *(const PG8_LAS bf16x8*)(lds + PG8_SA(b, h) + aoff + m * 2048 + k * 1024); } while (0)
; #define PG8_MMA(ai, bj, At, Bt) do { __builtin_amdgcn_s_setprio(1); _Pragma("unroll") for (int m = 0; m < 4; ++m) _Pragma("unroll") for (int n = 0; n < 2; ++n) _Pragma("unroll") for (int k = 0; k < 2; ++k) \
;         acc[ai][bj][m][n] = __builtin_amdgcn_mfma_f32_16x16x32_bf16(Bt[n][k], At[m][k], acc[ai][bj][m][n], 0, 0, 0); __builtin_amdgcn_s_setprio(0); } while (0)
; #define PG8_WAIT_V(n) asm volatile("s_waitcnt vmcnt(" #n ")" ::: "memory")
; #define PG8_WAIT_L(n) asm volatile("s_waitcnt lgkmcnt(" #n ")" ::: "memory")
; #define PG8_BAR __builtin_amdgcn_s_barrier()
; #define PG8_SCHED __builtin_amdgcn_sched_barrier(0)
; template <class Epi, class Sched, bool ALIGN_EPI = false, bool SP2 = false>
; __device__ __forceinline__ void gemm_phase(PG8_LAS unsigned char* lds, const Gemm g, const Sched& S, const Epi& E) {
;     ...
;         for (int t = 0; t < nt; t += 2) {
;             if constexpr (Epi::HAS_MID) { if (t == Epi::MID_T) E.mid(acc, cur, wr, wc, fr, fq); }
;             const bool last = (t == nt - 2);
;     ...
;             PG8_LDA(At, 1, 1); PG8_STAGE(PG8_SB(1, 0), b3, voffB); PG8_STAGE(PG8_SB(1, 1), b3 + hstep, voffB); PG8_STAGE(PG8_SA(1, 0), a3, voffA);
;             PG8_WAIT_V(8); PG8_WAIT_L(0); PG8_BAR; PG8_MMA(1, 0, At, B0); PG8_MMA(1, 1, At, B1); PG8_BAR; PG8_SCHED;
	s_add_i32 s50, s71, s53
	v_lshl_add_u64 v[176:177], v[176:177], 0, s[12:13]
	s_mov_b32 m0, s50
	ds_read_b128 v[172:175], v183 offset:49152
	ds_read_b128 v[188:191], v183 offset:50176
	ds_read_b128 v[192:195], v183 offset:51200
	ds_read_b128 v[196:199], v183 offset:52224
	ds_read_b128 v[200:203], v183 offset:53248
	ds_read_b128 v[204:207], v183 offset:54272
	ds_read_b128 v[208:211], v183 offset:55296
	ds_read_b128 v[212:215], v183 offset:56320
	global_load_lds_dwordx4 v[176:177], off
	s_add_i32 m0, s50, 0x2000
	s_add_u32 s48, s48, 0x40080
	v_lshl_add_u64 v[176:177], v[216:217], 0, s[12:13]
	s_addc_u32 s49, s49, 0
	s_add_i32 s50, s72, s53
	global_load_lds_dwordx4 v[176:177], off
	v_lshl_add_u64 v[176:177], s[48:49], 0, v[128:129]
	s_mov_b32 m0, s50
	s_nop 0
	global_load_lds_dwordx4 v[176:177], off
	v_lshl_add_u64 v[176:177], s[48:49], 0, v[130:131]
	s_add_i32 m0, s50, 0x2000
	s_nop 0
	global_load_lds_dwordx4 v[176:177], off
	v_lshl_add_u64 v[176:177], v[218:219], 0, s[12:13]
	s_mov_b32 m0, s61
	s_nop 0
	global_load_lds_dwordx4 v[176:177], off
	v_lshl_add_u64 v[176:177], v[220:221], 0, s[12:13]
	s_mov_b32 m0, s62
	s_nop 0
	global_load_lds_dwordx4 v[176:177], off
	s_waitcnt vmcnt(8)
	s_waitcnt lgkmcnt(0)
	s_barrier
	s_waitcnt lgkmcnt(0)
	v_mfma_f32_16x16x32_bf16 v[60:63], v[140:143], v[172:175], v[60:63]
	v_mfma_f32_16x16x32_bf16 v[56:59], v[148:151], v[172:175], v[56:59]
	v_mfma_f32_16x16x32_bf16 v[44:47], v[140:143], v[192:195], v[44:47]
	v_mfma_f32_16x16x32_bf16 v[40:43], v[148:151], v[192:195], v[40:43]
	v_mfma_f32_16x16x32_bf16 v[28:31], v[140:143], v[200:203], v[28:31]
	v_mfma_f32_16x16x32_bf16 v[24:27], v[148:151], v[200:203], v[24:27]
	v_mfma_f32_16x16x32_bf16 v[12:15], v[140:143], v[208:211], v[12:15]
	v_mfma_f32_16x16x32_bf16 v[8:11], v[148:151], v[208:211], v[8:11]
	v_mfma_f32_16x16x32_bf16 v[60:63], v[144:147], v[188:191], v[60:63]
	v_mfma_f32_16x16x32_bf16 v[56:59], v[152:155], v[188:191], v[56:59]
	v_mfma_f32_16x16x32_bf16 v[44:47], v[144:147], v[196:199], v[44:47]
	v_mfma_f32_16x16x32_bf16 v[40:43], v[152:155], v[196:199], v[40:43]
	v_mfma_f32_16x16x32_bf16 v[28:31], v[144:147], v[204:207], v[28:31]
	v_mfma_f32_16x16x32_bf16 v[24:27], v[152:155], v[204:207], v[24:27]
	v_mfma_f32_16x16x32_bf16 v[12:15], v[144:147], v[212:215], v[12:15]
	v_mfma_f32_16x16x32_bf16 v[8:11], v[152:155], v[212:215], v[8:11]
	v_mfma_f32_16x16x32_bf16 v[52:55], v[156:159], v[172:175], v[52:55]
	v_mfma_f32_16x16x32_bf16 v[48:51], v[164:167], v[172:175], v[48:51]
	v_mfma_f32_16x16x32_bf16 v[36:39], v[156:159], v[192:195], v[36:39]
	v_mfma_f32_16x16x32_bf16 v[32:35], v[164:167], v[192:195], v[32:35]
	v_mfma_f32_16x16x32_bf16 v[20:23], v[156:159], v[200:203], v[20:23]
	v_mfma_f32_16x16x32_bf16 v[16:19], v[164:167], v[200:203], v[16:19]
	v_mfma_f32_16x16x32_bf16 v[4:7], v[156:159], v[208:211], v[4:7]
	v_mfma_f32_16x16x32_bf16 v[0:3], v[164:167], v[208:211], v[0:3]
	v_mfma_f32_16x16x32_bf16 v[52:55], v[160:163], v[188:191], v[52:55]
	v_mfma_f32_16x16x32_bf16 v[48:51], v[168:171], v[188:191], v[48:51]
	v_mfma_f32_16x16x32_bf16 v[36:39], v[160:163], v[196:199], v[36:39]
	v_mfma_f32_16x16x32_bf16 v[32:35], v[168:171], v[196:199], v[32:35]
	v_mfma_f32_16x16x32_bf16 v[20:23], v[160:163], v[204:207], v[20:23]
	v_mfma_f32_16x16x32_bf16 v[16:19], v[168:171], v[204:207], v[16:19]
	v_mfma_f32_16x16x32_bf16 v[4:7], v[160:163], v[212:215], v[4:7]
	v_mfma_f32_16x16x32_bf16 v[0:3], v[168:171], v[212:215], v[0:3]
	s_barrier
	s_add_i32 s70, s70, 2
	s_add_u32 s46, s46, 0x100
	s_addc_u32 s47, s47, 0
	s_add_u32 s68, s68, 0x100
	s_addc_u32 s69, s69, 0
	s_cmp_gt_u32 s70, 13
	s_cbranch_scc0 .LBB0_558
	s_and_b64 vcc, exec, s[14:15]
	s_cbranch_vccz .LBB0_561
	s_barrier
